# GEMM K loops: first eight fragment ds_reads issued at the loop top (literal stage offsets), ahead of the SALU pointer-select block that sat between the loop-back barrier and the first LDS read
# speedup vs baseline: 1.0034x; 1.0034x over previous
; #define PG8_STAGE(bufoff, gbase, voff) do { _Pragma("unroll") for (int _i = 0; _i < 2; ++_i) \
;         __builtin_amdgcn_global_load_lds((const unsigned*)((const char*)(gbase) + (voff)[_i]), (PG8_LAS unsigned*)(lds + (bufoff) + ldsw + _i * 8192), 16, 0, 0); } while (0)
; #define PG8_LDA(dst, b, h) do { _Pragma("unroll") for (int m = 0; m < 4; ++m) _Pragma("unroll") for (int k = 0; k < 2; ++k) dst[m][k] = *(const PG8_LAS bf16x8*)(lds + PG8_SA(b, h) + aoff + m * 2048 + k * 1024); } while (0)
; #define PG8_LDB(dst, b, h) do { _Pragma("unroll") for (int n = 0; n < 2; ++n) _Pragma("unroll") for (int k = 0; k < 2; ++k) dst[n][k] = *(const PG8_LAS bf16x8*)(lds + PG8_SB(b, h) + boff + n * 2048 + k * 1024); } while (0)
; #define PG8_MMA(ai, bj, At, Bt) do { __builtin_amdgcn_s_setprio(1); _Pragma("unroll") for (int m = 0; m < 4; ++m) _Pragma("unroll") for (int n = 0; n < 2; ++n) _Pragma("unroll") for (int k = 0; k < 2; ++k) \
;         acc[ai][bj][m][n] = __builtin_amdgcn_mfma_f32_16x16x32_bf16(Bt[n][k], At[m][k], acc[ai][bj][m][n], 0, 0, 0); __builtin_amdgcn_s_setprio(0); } while (0)
; #define PG8_WAIT_V(n) asm volatile("s_waitcnt vmcnt(" #n ")" ::: "memory")
; #define PG8_WAIT_L(n) asm volatile("s_waitcnt lgkmcnt(" #n ")" ::: "memory")
; #define PG8_BAR __builtin_amdgcn_s_barrier()
; #define PG8_SCHED __builtin_amdgcn_sched_barrier(0)
; template <class Epi, class Sched, bool ALIGN_EPI = false, bool SP2 = false>
; __device__ __forceinline__ void gemm_phase(PG8_LAS unsigned char* lds, const Gemm g, const Sched S, const Epi E) {
;     ...
;             const bool last = (t == nt - 2);
;             const char* a1 = cA + (size_t)(t + 1) * kstep;
;             const char* a2 = last ? nA : cA + (size_t)(t + 2) * kstep; const char* b2 = last ? nB : cB + (size_t)(t + 2) * kstep;
;             const char* a3 = a2 + kstep; const char* b3 = b2 + kstep;
;             if (last && has_next) S.a_ready(nxt);
;             if constexpr (SP2) {
;             PG8_LDB(B0, 0, 0); PG8_LDB(B1, 0, 1); PG8_SCHED; PG8_LDA(At, 0, 0); PG8_STAGE(PG8_SA(1, 1), a1 + hstep, voffA);
;             PG8_WAIT_V(8); PG8_WAIT_L(0); PG8_BAR; PG8_MMA(0, 0, At, B0); PG8_MMA(0, 1, At, B1); PG8_BAR; PG8_SCHED;
;             PG8_LDA(At, 0, 1); PG8_STAGE(PG8_SB(0, 0), b2, voffB); PG8_STAGE(PG8_SB(0, 1), b2 + hstep, voffB); PG8_STAGE(PG8_SA(0, 0), a2, voffA);
.LBB0_180:
	v_add_u32_e32 v140, 0x10000, v143
	ds_read_b128 v[154:157], v140
	ds_read_b128 v[158:161], v140 offset:1024
	ds_read_b128 v[162:165], v140 offset:2048
	ds_read_b128 v[166:169], v140 offset:3072
	v_add_u32_e32 v140, 0x14000, v143
	ds_read_b128 v[170:173], v140
	ds_read_b128 v[174:177], v140 offset:1024
	ds_read_b128 v[182:185], v140 offset:2048
	ds_read_b128 v[198:201], v140 offset:3072
	s_add_i32 s20, s18, 2
	s_add_u32 s21, s16, 0x80
	s_addc_u32 s19, s17, 0
	s_add_i32 s25, 0, 0x10000
	s_cmp_eq_u32 s75, s18
	s_cselect_b32 s19, s1, s19
	s_cselect_b32 s18, s0, s21
	s_cselect_b32 s23, s59, s15
	s_cselect_b32 s22, s58, s14
	s_add_i32 s21, 0, 0x14000
	v_lshl_add_u64 v[140:141], s[16:17], 0, v[136:137]
	s_add_i32 m0, s68, 0xc000
	ds_read_b128 v[202:205], v146
	ds_read_b128 v[206:209], v146 offset:1024
	ds_read_b128 v[210:213], v146 offset:2048
	ds_read_b128 v[214:217], v146 offset:3072
	ds_read_b128 v[218:221], v146 offset:4096
	ds_read_b128 v[222:225], v146 offset:5120
	ds_read_b128 v[226:229], v146 offset:6144
	ds_read_b128 v[230:233], v146 offset:7168
	global_load_lds_dwordx4 v[140:141], off
	v_lshl_add_u64 v[140:141], s[16:17], 0, v[138:139]
	s_add_i32 m0, s68, 0xe000
	s_nop 0
	global_load_lds_dwordx4 v[140:141], off
	s_waitcnt vmcnt(8)
	s_waitcnt lgkmcnt(0)
	s_barrier
	s_setprio 1
	s_waitcnt lgkmcnt(0)
	v_mfma_f32_16x16x32_bf16 v[126:129], v[154:157], v[202:205], v[126:129]
	v_mfma_f32_16x16x32_bf16 v[118:121], v[162:165], v[202:205], v[118:121]
	v_mfma_f32_16x16x32_bf16 v[110:113], v[154:157], v[210:213], v[110:113]
	v_mfma_f32_16x16x32_bf16 v[102:105], v[162:165], v[210:213], v[102:105]
	v_mfma_f32_16x16x32_bf16 v[94:97], v[154:157], v[218:221], v[94:97]
	v_mfma_f32_16x16x32_bf16 v[86:89], v[162:165], v[218:221], v[86:89]
	v_mfma_f32_16x16x32_bf16 v[78:81], v[154:157], v[226:229], v[78:81]
	v_mfma_f32_16x16x32_bf16 v[70:73], v[162:165], v[226:229], v[70:73]
	v_mfma_f32_16x16x32_bf16 v[126:129], v[158:161], v[206:209], v[126:129]
	v_mfma_f32_16x16x32_bf16 v[118:121], v[166:169], v[206:209], v[118:121]
	v_mfma_f32_16x16x32_bf16 v[110:113], v[158:161], v[214:217], v[110:113]
	v_mfma_f32_16x16x32_bf16 v[102:105], v[166:169], v[214:217], v[102:105]
	v_mfma_f32_16x16x32_bf16 v[94:97], v[158:161], v[222:225], v[94:97]
	v_mfma_f32_16x16x32_bf16 v[86:89], v[166:169], v[222:225], v[86:89]
	v_mfma_f32_16x16x32_bf16 v[78:81], v[158:161], v[230:233], v[78:81]
	v_mfma_f32_16x16x32_bf16 v[70:73], v[166:169], v[230:233], v[70:73]
	s_setprio 0
	s_setprio 1
	v_mfma_f32_16x16x32_bf16 v[122:125], v[170:173], v[202:205], v[122:125]
	v_mfma_f32_16x16x32_bf16 v[114:117], v[182:185], v[202:205], v[114:117]
	v_mfma_f32_16x16x32_bf16 v[106:109], v[170:173], v[210:213], v[106:109]
	v_mfma_f32_16x16x32_bf16 v[98:101], v[182:185], v[210:213], v[98:101]
	v_mfma_f32_16x16x32_bf16 v[90:93], v[170:173], v[218:221], v[90:93]
	v_mfma_f32_16x16x32_bf16 v[82:85], v[182:185], v[218:221], v[82:85]
	v_mfma_f32_16x16x32_bf16 v[74:77], v[170:173], v[226:229], v[74:77]
	v_mfma_f32_16x16x32_bf16 v[66:69], v[182:185], v[226:229], v[66:69]
	v_mfma_f32_16x16x32_bf16 v[122:125], v[174:177], v[206:209], v[122:125]
	v_mfma_f32_16x16x32_bf16 v[114:117], v[198:201], v[206:209], v[114:117]
	v_mfma_f32_16x16x32_bf16 v[106:109], v[174:177], v[214:217], v[106:109]
	v_mfma_f32_16x16x32_bf16 v[98:101], v[198:201], v[214:217], v[98:101]
	v_mfma_f32_16x16x32_bf16 v[90:93], v[174:177], v[222:225], v[90:93]
	v_mfma_f32_16x16x32_bf16 v[82:85], v[198:201], v[222:225], v[82:85]
	v_mfma_f32_16x16x32_bf16 v[74:77], v[174:177], v[230:233], v[74:77]
	v_mfma_f32_16x16x32_bf16 v[66:69], v[198:201], v[230:233], v[66:69]
	s_setprio 0
	s_barrier
	s_add_i32 s25, s25, s61
	v_lshl_add_u64 v[140:141], s[22:23], 0, v[0:1]
	s_mov_b32 m0, s25
	ds_read_b128 v[202:205], v146 offset:16384
	ds_read_b128 v[206:209], v146 offset:17408
	ds_read_b128 v[210:213], v146 offset:18432
	ds_read_b128 v[214:217], v146 offset:19456
	ds_read_b128 v[218:221], v146 offset:20480
	ds_read_b128 v[222:225], v146 offset:21504
	ds_read_b128 v[226:229], v146 offset:22528
	ds_read_b128 v[230:233], v146 offset:23552
	global_load_lds_dwordx4 v[140:141], off
	s_add_i32 m0, s25, 0x2000
	v_lshl_add_u64 v[234:235], s[22:23], 0, v[130:131]
	s_add_u32 s22, s22, s28
	s_addc_u32 s23, s23, 0
	s_add_i32 s21, s21, s61
	global_load_lds_dwordx4 v[234:235], off
	v_lshl_add_u64 v[236:237], s[22:23], 0, v[0:1]
	s_mov_b32 m0, s21
	v_lshl_add_u64 v[238:239], s[22:23], 0, v[130:131]
	global_load_lds_dwordx4 v[236:237], off
	s_add_i32 m0, s21, 0x2000
	v_lshl_add_u64 v[240:241], s[18:19], 0, v[134:135]
	global_load_lds_dwordx4 v[238:239], off
	s_mov_b32 m0, s68
	v_lshl_add_u64 v[242:243], s[18:19], 0, v[132:133]
	global_load_lds_dwordx4 v[240:241], off
	s_mov_b32 m0, s69
	s_nop 0
	global_load_lds_dwordx4 v[242:243], off
	s_waitcnt vmcnt(8)
	s_waitcnt lgkmcnt(0)
	s_barrier
; #define PG8_STAGE(bufoff, gbase, voff) do { _Pragma("unroll") for (int _i = 0; _i < 2; ++_i) \
;         __builtin_amdgcn_global_load_lds((const unsigned*)((const char*)(gbase) + (voff)[_i]), (PG8_LAS unsigned*)(lds + (bufoff) + ldsw + _i * 8192), 16, 0, 0); } while (0)
; #define PG8_LDA(dst, b, h) do { _Pragma("unroll") for (int m = 0; m < 4; ++m) _Pragma("unroll") for (int k = 0; k < 2; ++k) dst[m][k] = *(const PG8_LAS bf16x8*)(lds + PG8_SA(b, h) + aoff + m * 2048 + k * 1024); } while (0)
; #define PG8_LDB(dst, b, h) do { _Pragma("unroll") for (int n = 0; n < 2; ++n) _Pragma("unroll") for (int k = 0; k < 2; ++k) dst[n][k] = *(const PG8_LAS bf16x8*)(lds + PG8_SB(b, h) + boff + n * 2048 + k * 1024); } while (0)
; #define PG8_MMA(ai, bj, At, Bt) do { __builtin_amdgcn_s_setprio(1); _Pragma("unroll") for (int m = 0; m < 4; ++m) _Pragma("unroll") for (int n = 0; n < 2; ++n) _Pragma("unroll") for (int k = 0; k < 2; ++k) \
;         acc[ai][bj][m][n] = __builtin_amdgcn_mfma_f32_16x16x32_bf16(Bt[n][k], At[m][k], acc[ai][bj][m][n], 0, 0, 0); __builtin_amdgcn_s_setprio(0); } while (0)
; #define PG8_WAIT_V(n) asm volatile("s_waitcnt vmcnt(" #n ")" ::: "memory")
; #define PG8_WAIT_L(n) asm volatile("s_waitcnt lgkmcnt(" #n ")" ::: "memory")
; #define PG8_BAR __builtin_amdgcn_s_barrier()
; #define PG8_SCHED __builtin_amdgcn_sched_barrier(0)
; template <class Epi, class Sched, bool ALIGN_EPI = false, bool SP2 = false>
; __device__ __forceinline__ void gemm_phase(PG8_LAS unsigned char* lds, const Gemm g, const Sched S, const Epi E) {
;     ...
;             PG8_WAIT_V(8); PG8_WAIT_L(0); PG8_BAR; PG8_MMA(1, 0, At, B0); PG8_MMA(1, 1, At, B1); PG8_BAR; PG8_SCHED;
;             PG8_LDB(B0, 1, 0); PG8_LDB(B1, 1, 1); PG8_SCHED; PG8_LDA(At, 1, 0); PG8_STAGE(PG8_SA(0, 1), a2 + hstep, voffA);
;             PG8_WAIT_V(8); PG8_WAIT_L(0); PG8_BAR; PG8_MMA(0, 0, At, B0); PG8_MMA(0, 1, At, B1); PG8_BAR; PG8_SCHED;
	s_setprio 1
	s_waitcnt lgkmcnt(0)
	v_mfma_f32_16x16x32_bf16 v[62:65], v[154:157], v[202:205], v[62:65]
	v_mfma_f32_16x16x32_bf16 v[54:57], v[162:165], v[202:205], v[54:57]
	v_mfma_f32_16x16x32_bf16 v[46:49], v[154:157], v[210:213], v[46:49]
	v_mfma_f32_16x16x32_bf16 v[38:41], v[162:165], v[210:213], v[38:41]
	v_mfma_f32_16x16x32_bf16 v[30:33], v[154:157], v[218:221], v[30:33]
	v_mfma_f32_16x16x32_bf16 v[22:25], v[162:165], v[218:221], v[22:25]
	v_mfma_f32_16x16x32_bf16 v[14:17], v[154:157], v[226:229], v[14:17]
	v_mfma_f32_16x16x32_bf16 v[6:9], v[162:165], v[226:229], v[6:9]
	v_mfma_f32_16x16x32_bf16 v[62:65], v[158:161], v[206:209], v[62:65]
	v_mfma_f32_16x16x32_bf16 v[54:57], v[166:169], v[206:209], v[54:57]
	v_mfma_f32_16x16x32_bf16 v[46:49], v[158:161], v[214:217], v[46:49]
	v_mfma_f32_16x16x32_bf16 v[38:41], v[166:169], v[214:217], v[38:41]
	v_mfma_f32_16x16x32_bf16 v[30:33], v[158:161], v[222:225], v[30:33]
	v_mfma_f32_16x16x32_bf16 v[22:25], v[166:169], v[222:225], v[22:25]
	v_mfma_f32_16x16x32_bf16 v[14:17], v[158:161], v[230:233], v[14:17]
	v_mfma_f32_16x16x32_bf16 v[6:9], v[166:169], v[230:233], v[6:9]
	s_setprio 0
	s_setprio 1
	v_mfma_f32_16x16x32_bf16 v[58:61], v[170:173], v[202:205], v[58:61]
	v_mfma_f32_16x16x32_bf16 v[50:53], v[182:185], v[202:205], v[50:53]
	v_mfma_f32_16x16x32_bf16 v[42:45], v[170:173], v[210:213], v[42:45]
	v_mfma_f32_16x16x32_bf16 v[34:37], v[182:185], v[210:213], v[34:37]
	v_mfma_f32_16x16x32_bf16 v[26:29], v[170:173], v[218:221], v[26:29]
	v_mfma_f32_16x16x32_bf16 v[18:21], v[182:185], v[218:221], v[18:21]
	v_mfma_f32_16x16x32_bf16 v[10:13], v[170:173], v[226:229], v[10:13]
	v_mfma_f32_16x16x32_bf16 v[2:5], v[182:185], v[226:229], v[2:5]
	v_mfma_f32_16x16x32_bf16 v[58:61], v[174:177], v[206:209], v[58:61]
	v_mfma_f32_16x16x32_bf16 v[50:53], v[198:201], v[206:209], v[50:53]
	v_mfma_f32_16x16x32_bf16 v[42:45], v[174:177], v[214:217], v[42:45]
	v_mfma_f32_16x16x32_bf16 v[34:37], v[198:201], v[214:217], v[34:37]
	v_mfma_f32_16x16x32_bf16 v[26:29], v[174:177], v[222:225], v[26:29]
	v_mfma_f32_16x16x32_bf16 v[18:21], v[198:201], v[222:225], v[18:21]
	v_mfma_f32_16x16x32_bf16 v[10:13], v[174:177], v[230:233], v[10:13]
	v_mfma_f32_16x16x32_bf16 v[2:5], v[198:201], v[230:233], v[2:5]
	s_setprio 0
	s_barrier
	s_add_i32 s21, 0, 0x18000
	s_add_i32 s22, 0, 0x1c000
	v_add_u32_e32 v166, s21, v143
	v_add_u32_e32 v186, s22, v143
	ds_read_b128 v[154:157], v166
	ds_read_b128 v[158:161], v166 offset:1024
	ds_read_b128 v[162:165], v166 offset:2048
	ds_read_b128 v[166:169], v166 offset:3072
	ds_read_b128 v[170:173], v186
	ds_read_b128 v[174:177], v186 offset:1024
	ds_read_b128 v[182:185], v186 offset:2048
	ds_read_b128 v[198:201], v186 offset:3072
	s_add_u32 s18, s18, s28
	s_addc_u32 s19, s19, 0
	s_mov_b32 m0, s70
	v_lshl_add_u64 v[244:245], s[18:19], 0, v[134:135]
	ds_read_b128 v[202:205], v146 offset:32768
	ds_read_b128 v[206:209], v146 offset:33792
	ds_read_b128 v[210:213], v146 offset:34816
	ds_read_b128 v[214:217], v146 offset:35840
	ds_read_b128 v[218:221], v146 offset:36864
	ds_read_b128 v[222:225], v146 offset:37888
	ds_read_b128 v[226:229], v146 offset:38912
	ds_read_b128 v[230:233], v146 offset:39936
	global_load_lds_dwordx4 v[244:245], off
	v_lshl_add_u64 v[244:245], s[18:19], 0, v[132:133]
	s_mov_b32 m0, s71
	s_nop 0
	global_load_lds_dwordx4 v[244:245], off
	s_waitcnt vmcnt(8)
	s_waitcnt lgkmcnt(0)
	s_barrier
	s_setprio 1
	s_waitcnt lgkmcnt(0)
	v_mfma_f32_16x16x32_bf16 v[126:129], v[154:157], v[202:205], v[126:129]
	v_mfma_f32_16x16x32_bf16 v[118:121], v[162:165], v[202:205], v[118:121]
	v_mfma_f32_16x16x32_bf16 v[110:113], v[154:157], v[210:213], v[110:113]
	v_mfma_f32_16x16x32_bf16 v[102:105], v[162:165], v[210:213], v[102:105]
	v_mfma_f32_16x16x32_bf16 v[94:97], v[154:157], v[218:221], v[94:97]
	v_mfma_f32_16x16x32_bf16 v[86:89], v[162:165], v[218:221], v[86:89]
	v_mfma_f32_16x16x32_bf16 v[78:81], v[154:157], v[226:229], v[78:81]
	v_mfma_f32_16x16x32_bf16 v[70:73], v[162:165], v[226:229], v[70:73]
	v_mfma_f32_16x16x32_bf16 v[126:129], v[158:161], v[206:209], v[126:129]
	v_mfma_f32_16x16x32_bf16 v[118:121], v[166:169], v[206:209], v[118:121]
	v_mfma_f32_16x16x32_bf16 v[110:113], v[158:161], v[214:217], v[110:113]
	v_mfma_f32_16x16x32_bf16 v[102:105], v[166:169], v[214:217], v[102:105]
	v_mfma_f32_16x16x32_bf16 v[94:97], v[158:161], v[222:225], v[94:97]
	v_mfma_f32_16x16x32_bf16 v[86:89], v[166:169], v[222:225], v[86:89]
	v_mfma_f32_16x16x32_bf16 v[78:81], v[158:161], v[230:233], v[78:81]
	v_mfma_f32_16x16x32_bf16 v[70:73], v[166:169], v[230:233], v[70:73]
	s_setprio 0
	s_setprio 1
	v_mfma_f32_16x16x32_bf16 v[122:125], v[170:173], v[202:205], v[122:125]
	v_mfma_f32_16x16x32_bf16 v[114:117], v[182:185], v[202:205], v[114:117]
	v_mfma_f32_16x16x32_bf16 v[106:109], v[170:173], v[210:213], v[106:109]
	v_mfma_f32_16x16x32_bf16 v[98:101], v[182:185], v[210:213], v[98:101]
	v_mfma_f32_16x16x32_bf16 v[90:93], v[170:173], v[218:221], v[90:93]
	v_mfma_f32_16x16x32_bf16 v[82:85], v[182:185], v[218:221], v[82:85]
	v_mfma_f32_16x16x32_bf16 v[74:77], v[170:173], v[226:229], v[74:77]
	v_mfma_f32_16x16x32_bf16 v[66:69], v[182:185], v[226:229], v[66:69]
	v_mfma_f32_16x16x32_bf16 v[122:125], v[174:177], v[206:209], v[122:125]
	v_mfma_f32_16x16x32_bf16 v[114:117], v[198:201], v[206:209], v[114:117]
	v_mfma_f32_16x16x32_bf16 v[106:109], v[174:177], v[214:217], v[106:109]
	v_mfma_f32_16x16x32_bf16 v[98:101], v[198:201], v[214:217], v[98:101]
	v_mfma_f32_16x16x32_bf16 v[90:93], v[174:177], v[222:225], v[90:93]
	v_mfma_f32_16x16x32_bf16 v[82:85], v[198:201], v[222:225], v[82:85]
	v_mfma_f32_16x16x32_bf16 v[74:77], v[174:177], v[230:233], v[74:77]
	v_mfma_f32_16x16x32_bf16 v[66:69], v[198:201], v[230:233], v[66:69]
	s_setprio 0
	s_barrier
; #define PG8_STAGE(bufoff, gbase, voff) do { _Pragma("unroll") for (int _i = 0; _i < 2; ++_i) \
;         __builtin_amdgcn_global_load_lds((const unsigned*)((const char*)(gbase) + (voff)[_i]), (PG8_LAS unsigned*)(lds + (bufoff) + ldsw + _i * 8192), 16, 0, 0); } while (0)
; #define PG8_LDA(dst, b, h) do { _Pragma("unroll") for (int m = 0; m < 4; ++m) _Pragma("unroll") for (int k = 0; k < 2; ++k) dst[m][k] = *(const PG8_LAS bf16x8*)(lds + PG8_SA(b, h) + aoff + m * 2048 + k * 1024); } while (0)
; #define PG8_MMA(ai, bj, At, Bt) do { __builtin_amdgcn_s_setprio(1); _Pragma("unroll") for (int m = 0; m < 4; ++m) _Pragma("unroll") for (int n = 0; n < 2; ++n) _Pragma("unroll") for (int k = 0; k < 2; ++k) \
;         acc[ai][bj][m][n] = __builtin_amdgcn_mfma_f32_16x16x32_bf16(Bt[n][k], At[m][k], acc[ai][bj][m][n], 0, 0, 0); __builtin_amdgcn_s_setprio(0); } while (0)
; #define PG8_WAIT_V(n) asm volatile("s_waitcnt vmcnt(" #n ")" ::: "memory")
; #define PG8_WAIT_L(n) asm volatile("s_waitcnt lgkmcnt(" #n ")" ::: "memory")
; #define PG8_BAR __builtin_amdgcn_s_barrier()
; #define PG8_SCHED __builtin_amdgcn_sched_barrier(0)
; template <class Epi, class Sched, bool ALIGN_EPI = false, bool SP2 = false>
; __device__ __forceinline__ void gemm_phase(PG8_LAS unsigned char* lds, const Gemm g, const Sched S, const Epi E) {
;     ...
;             PG8_LDA(At, 1, 1); PG8_STAGE(PG8_SB(1, 0), b3, voffB); PG8_STAGE(PG8_SB(1, 1), b3 + hstep, voffB); PG8_STAGE(PG8_SA(1, 0), a3, voffA);
;             PG8_WAIT_V(8); PG8_WAIT_L(0); PG8_BAR; PG8_MMA(1, 0, At, B0); PG8_MMA(1, 1, At, B1); PG8_BAR; PG8_SCHED;
	s_add_i32 s18, s21, s61
	v_lshl_add_u64 v[140:141], v[140:141], 0, s[12:13]
	s_mov_b32 m0, s18
	ds_read_b128 v[202:205], v146 offset:49152
	ds_read_b128 v[206:209], v146 offset:50176
	ds_read_b128 v[210:213], v146 offset:51200
	ds_read_b128 v[214:217], v146 offset:52224
	ds_read_b128 v[218:221], v146 offset:53248
	ds_read_b128 v[222:225], v146 offset:54272
	ds_read_b128 v[226:229], v146 offset:55296
	ds_read_b128 v[230:233], v146 offset:56320
	global_load_lds_dwordx4 v[140:141], off
	v_lshl_add_u64 v[140:141], v[234:235], 0, s[12:13]
	s_add_i32 m0, s18, 0x2000
	s_add_i32 s18, s22, s61
	global_load_lds_dwordx4 v[140:141], off
	v_lshl_add_u64 v[140:141], v[236:237], 0, s[12:13]
	s_mov_b32 m0, s18
	s_nop 0
	global_load_lds_dwordx4 v[140:141], off
	v_lshl_add_u64 v[140:141], v[238:239], 0, s[12:13]
	s_add_i32 m0, s18, 0x2000
	s_nop 0
	global_load_lds_dwordx4 v[140:141], off
	v_lshl_add_u64 v[140:141], v[240:241], 0, s[12:13]
	s_mov_b32 m0, s73
	s_nop 0
	global_load_lds_dwordx4 v[140:141], off
	v_lshl_add_u64 v[140:141], v[242:243], 0, s[12:13]
	s_mov_b32 m0, s74
	s_nop 0
	global_load_lds_dwordx4 v[140:141], off
	s_waitcnt vmcnt(8)
	s_waitcnt lgkmcnt(0)
	s_barrier
	s_setprio 1
	s_waitcnt lgkmcnt(0)
	v_mfma_f32_16x16x32_bf16 v[62:65], v[154:157], v[202:205], v[62:65]
	v_mfma_f32_16x16x32_bf16 v[54:57], v[162:165], v[202:205], v[54:57]
	v_mfma_f32_16x16x32_bf16 v[46:49], v[154:157], v[210:213], v[46:49]
	v_mfma_f32_16x16x32_bf16 v[38:41], v[162:165], v[210:213], v[38:41]
	v_mfma_f32_16x16x32_bf16 v[30:33], v[154:157], v[218:221], v[30:33]
	v_mfma_f32_16x16x32_bf16 v[22:25], v[162:165], v[218:221], v[22:25]
	v_mfma_f32_16x16x32_bf16 v[14:17], v[154:157], v[226:229], v[14:17]
	v_mfma_f32_16x16x32_bf16 v[6:9], v[162:165], v[226:229], v[6:9]
	v_mfma_f32_16x16x32_bf16 v[62:65], v[158:161], v[206:209], v[62:65]
	v_mfma_f32_16x16x32_bf16 v[54:57], v[166:169], v[206:209], v[54:57]
	v_mfma_f32_16x16x32_bf16 v[46:49], v[158:161], v[214:217], v[46:49]
	v_mfma_f32_16x16x32_bf16 v[38:41], v[166:169], v[214:217], v[38:41]
	v_mfma_f32_16x16x32_bf16 v[30:33], v[158:161], v[222:225], v[30:33]
	v_mfma_f32_16x16x32_bf16 v[22:25], v[166:169], v[222:225], v[22:25]
	v_mfma_f32_16x16x32_bf16 v[14:17], v[158:161], v[230:233], v[14:17]
	v_mfma_f32_16x16x32_bf16 v[6:9], v[166:169], v[230:233], v[6:9]
	s_setprio 0
	s_setprio 1
	v_mfma_f32_16x16x32_bf16 v[58:61], v[170:173], v[202:205], v[58:61]
	v_mfma_f32_16x16x32_bf16 v[50:53], v[182:185], v[202:205], v[50:53]
	v_mfma_f32_16x16x32_bf16 v[42:45], v[170:173], v[210:213], v[42:45]
	v_mfma_f32_16x16x32_bf16 v[34:37], v[182:185], v[210:213], v[34:37]
	v_mfma_f32_16x16x32_bf16 v[26:29], v[170:173], v[218:221], v[26:29]
	v_mfma_f32_16x16x32_bf16 v[18:21], v[182:185], v[218:221], v[18:21]
	v_mfma_f32_16x16x32_bf16 v[10:13], v[170:173], v[226:229], v[10:13]
	v_mfma_f32_16x16x32_bf16 v[2:5], v[182:185], v[226:229], v[2:5]
	v_mfma_f32_16x16x32_bf16 v[58:61], v[174:177], v[206:209], v[58:61]
	v_mfma_f32_16x16x32_bf16 v[50:53], v[198:201], v[206:209], v[50:53]
	v_mfma_f32_16x16x32_bf16 v[42:45], v[174:177], v[214:217], v[42:45]
	v_mfma_f32_16x16x32_bf16 v[34:37], v[198:201], v[214:217], v[34:37]
	v_mfma_f32_16x16x32_bf16 v[26:29], v[174:177], v[222:225], v[26:29]
	v_mfma_f32_16x16x32_bf16 v[18:21], v[198:201], v[222:225], v[18:21]
	v_mfma_f32_16x16x32_bf16 v[10:13], v[174:177], v[230:233], v[10:13]
	v_mfma_f32_16x16x32_bf16 v[2:5], v[198:201], v[230:233], v[2:5]
	s_setprio 0
	s_add_u32 s16, s16, 0x100
	s_addc_u32 s17, s17, 0
	s_add_u32 s14, s14, 0x100
	s_addc_u32 s15, s15, 0
	s_cmp_ge_u32 s20, s72
	s_mov_b32 s18, s20
	s_barrier
	s_cbranch_scc0 .LBB0_180
	s_and_b64 vcc, exec, s[56:57]
	s_cbranch_vccz .LBB0_183
	s_barrier

; #define PG8_STAGE(bufoff, gbase, voff) do { _Pragma("unroll") for (int _i = 0; _i < 2; ++_i) \
;         __builtin_amdgcn_global_load_lds((const unsigned*)((const char*)(gbase) + (voff)[_i]), (PG8_LAS unsigned*)(lds + (bufoff) + ldsw + _i * 8192), 16, 0, 0); } while (0)
; #define PG8_LDA(dst, b, h) do { _Pragma("unroll") for (int m = 0; m < 4; ++m) _Pragma("unroll") for (int k = 0; k < 2; ++k) dst[m][k] = *(const PG8_LAS bf16x8*)(lds + PG8_SA(b, h) + aoff + m * 2048 + k * 1024); } while (0)
; #define PG8_LDB(dst, b, h) do { _Pragma("unroll") for (int n = 0; n < 2; ++n) _Pragma("unroll") for (int k = 0; k < 2; ++k) dst[n][k] = *(const PG8_LAS bf16x8*)(lds + PG8_SB(b, h) + boff + n * 2048 + k * 1024); } while (0)
; #define PG8_MMA(ai, bj, At, Bt) do { __builtin_amdgcn_s_setprio(1); _Pragma("unroll") for (int m = 0; m < 4; ++m) _Pragma("unroll") for (int n = 0; n < 2; ++n) _Pragma("unroll") for (int k = 0; k < 2; ++k) \
;         acc[ai][bj][m][n] = __builtin_amdgcn_mfma_f32_16x16x32_bf16(Bt[n][k], At[m][k], acc[ai][bj][m][n], 0, 0, 0); __builtin_amdgcn_s_setprio(0); } while (0)
; #define PG8_WAIT_V(n) asm volatile("s_waitcnt vmcnt(" #n ")" ::: "memory")
; #define PG8_WAIT_L(n) asm volatile("s_waitcnt lgkmcnt(" #n ")" ::: "memory")
; #define PG8_BAR __builtin_amdgcn_s_barrier()
; #define PG8_SCHED __builtin_amdgcn_sched_barrier(0)
; template <class Epi, class Sched, bool ALIGN_EPI = false, bool SP2 = false>
; __device__ __forceinline__ void gemm_phase(PG8_LAS unsigned char* lds, const Gemm g, const Sched S, const Epi E) {
;     ...
;             const bool last = (t == nt - 2);
;             const char* a1 = cA + (size_t)(t + 1) * kstep;
;             const char* a2 = last ? nA : cA + (size_t)(t + 2) * kstep; const char* b2 = last ? nB : cB + (size_t)(t + 2) * kstep;
;             const char* a3 = a2 + kstep; const char* b3 = b2 + kstep;
;             if (last && has_next) S.a_ready(nxt);
;             if constexpr (SP2) {
;             PG8_LDB(B0, 0, 0); PG8_LDB(B1, 0, 1); PG8_SCHED; PG8_LDA(At, 0, 0); PG8_STAGE(PG8_SA(1, 1), a1 + hstep, voffA);
;             PG8_WAIT_V(8); PG8_WAIT_L(0); PG8_BAR; PG8_MMA(0, 0, At, B0); PG8_MMA(0, 1, At, B1); PG8_BAR; PG8_SCHED;
;             PG8_LDA(At, 0, 1); PG8_STAGE(PG8_SB(0, 0), b2, voffB); PG8_STAGE(PG8_SB(0, 1), b2 + hstep, voffB); PG8_STAGE(PG8_SA(0, 0), a2, voffA);
.LBB0_224:
	v_add_u32_e32 v141, 0x10000, v147
	ds_read_b128 v[154:157], v141
	ds_read_b128 v[158:161], v141 offset:1024
	ds_read_b128 v[162:165], v141 offset:2048
	ds_read_b128 v[166:169], v141 offset:3072
	v_add_u32_e32 v141, 0x14000, v147
	ds_read_b128 v[170:173], v141
	ds_read_b128 v[174:177], v141 offset:1024
	ds_read_b128 v[182:185], v141 offset:2048
	ds_read_b128 v[198:201], v141 offset:3072
	s_add_i32 s21, s20, 2
	s_add_u32 s22, s30, 0x80
	s_addc_u32 s23, s31, 0
	s_add_i32 s26, 0, 0x10000
	s_cmp_eq_u32 s81, s20
	s_cselect_b32 s75, s1, s23
	s_cselect_b32 s74, s0, s22
	s_cselect_b32 s23, s19, s15
	s_cselect_b32 s22, s18, s14
	s_add_i32 s20, 0, 0x14000
	v_lshl_add_u64 v[234:235], s[30:31], 0, v[136:137]
	s_add_i32 m0, s85, 0xc000
	ds_read_b128 v[202:205], v152
	ds_read_b128 v[206:209], v152 offset:1024
	ds_read_b128 v[210:213], v152 offset:2048
	ds_read_b128 v[214:217], v152 offset:3072
	ds_read_b128 v[218:221], v152 offset:4096
	ds_read_b128 v[222:225], v152 offset:5120
	ds_read_b128 v[226:229], v152 offset:6144
	ds_read_b128 v[230:233], v152 offset:7168
	global_load_lds_dwordx4 v[234:235], off
	v_lshl_add_u64 v[234:235], s[30:31], 0, v[138:139]
	s_add_i32 m0, s85, 0xe000
	s_nop 0
	global_load_lds_dwordx4 v[234:235], off
	s_waitcnt vmcnt(8)
	s_waitcnt lgkmcnt(0)
	s_barrier
	s_setprio 1
	s_waitcnt lgkmcnt(0)
	v_mfma_f32_16x16x32_bf16 v[126:129], v[154:157], v[202:205], v[126:129]
	v_mfma_f32_16x16x32_bf16 v[122:125], v[162:165], v[202:205], v[122:125]
	v_mfma_f32_16x16x32_bf16 v[110:113], v[154:157], v[210:213], v[110:113]
	v_mfma_f32_16x16x32_bf16 v[106:109], v[162:165], v[210:213], v[106:109]
	v_mfma_f32_16x16x32_bf16 v[94:97], v[154:157], v[218:221], v[94:97]
	v_mfma_f32_16x16x32_bf16 v[90:93], v[162:165], v[218:221], v[90:93]
	v_mfma_f32_16x16x32_bf16 v[78:81], v[154:157], v[226:229], v[78:81]
	v_mfma_f32_16x16x32_bf16 v[74:77], v[162:165], v[226:229], v[74:77]
	v_mfma_f32_16x16x32_bf16 v[126:129], v[158:161], v[206:209], v[126:129]
	v_mfma_f32_16x16x32_bf16 v[122:125], v[166:169], v[206:209], v[122:125]
	v_mfma_f32_16x16x32_bf16 v[110:113], v[158:161], v[214:217], v[110:113]
	v_mfma_f32_16x16x32_bf16 v[106:109], v[166:169], v[214:217], v[106:109]
	v_mfma_f32_16x16x32_bf16 v[94:97], v[158:161], v[222:225], v[94:97]
	v_mfma_f32_16x16x32_bf16 v[90:93], v[166:169], v[222:225], v[90:93]
	v_mfma_f32_16x16x32_bf16 v[78:81], v[158:161], v[230:233], v[78:81]
	v_mfma_f32_16x16x32_bf16 v[74:77], v[166:169], v[230:233], v[74:77]
	s_setprio 0
	s_setprio 1
	v_mfma_f32_16x16x32_bf16 v[118:121], v[170:173], v[202:205], v[118:121]
	v_mfma_f32_16x16x32_bf16 v[114:117], v[182:185], v[202:205], v[114:117]
	v_mfma_f32_16x16x32_bf16 v[102:105], v[170:173], v[210:213], v[102:105]
	v_mfma_f32_16x16x32_bf16 v[98:101], v[182:185], v[210:213], v[98:101]
	v_mfma_f32_16x16x32_bf16 v[86:89], v[170:173], v[218:221], v[86:89]
	v_mfma_f32_16x16x32_bf16 v[82:85], v[182:185], v[218:221], v[82:85]
	v_mfma_f32_16x16x32_bf16 v[70:73], v[170:173], v[226:229], v[70:73]
	v_mfma_f32_16x16x32_bf16 v[66:69], v[182:185], v[226:229], v[66:69]
	v_mfma_f32_16x16x32_bf16 v[118:121], v[174:177], v[206:209], v[118:121]
	v_mfma_f32_16x16x32_bf16 v[114:117], v[198:201], v[206:209], v[114:117]
	v_mfma_f32_16x16x32_bf16 v[102:105], v[174:177], v[214:217], v[102:105]
	v_mfma_f32_16x16x32_bf16 v[98:101], v[198:201], v[214:217], v[98:101]
	v_mfma_f32_16x16x32_bf16 v[86:89], v[174:177], v[222:225], v[86:89]
	v_mfma_f32_16x16x32_bf16 v[82:85], v[198:201], v[222:225], v[82:85]
	v_mfma_f32_16x16x32_bf16 v[70:73], v[174:177], v[230:233], v[70:73]
	v_mfma_f32_16x16x32_bf16 v[66:69], v[198:201], v[230:233], v[66:69]
	s_setprio 0
	s_barrier
	s_add_i32 s26, s26, s84
	v_lshl_add_u64 v[234:235], s[22:23], 0, v[0:1]
	s_mov_b32 m0, s26
	ds_read_b128 v[202:205], v152 offset:16384
	ds_read_b128 v[206:209], v152 offset:17408
	ds_read_b128 v[210:213], v152 offset:18432
	ds_read_b128 v[214:217], v152 offset:19456
	ds_read_b128 v[218:221], v152 offset:20480
	ds_read_b128 v[222:225], v152 offset:21504
	ds_read_b128 v[226:229], v152 offset:22528
	ds_read_b128 v[230:233], v152 offset:23552
	global_load_lds_dwordx4 v[234:235], off
	s_add_i32 m0, s26, 0x2000
	v_lshl_add_u64 v[236:237], s[22:23], 0, v[134:135]
	s_add_u32 s22, s22, s52
	s_addc_u32 s23, s23, 0
	s_add_i32 s20, s20, s84
	global_load_lds_dwordx4 v[236:237], off
	v_lshl_add_u64 v[238:239], s[22:23], 0, v[0:1]
	s_mov_b32 m0, s20
	v_lshl_add_u64 v[240:241], s[22:23], 0, v[134:135]
	global_load_lds_dwordx4 v[238:239], off
	s_add_i32 m0, s20, 0x2000
	v_lshl_add_u64 v[242:243], s[74:75], 0, v[130:131]
	global_load_lds_dwordx4 v[240:241], off
	s_mov_b32 m0, s85
	v_lshl_add_u64 v[244:245], s[74:75], 0, v[132:133]
	global_load_lds_dwordx4 v[242:243], off
	s_mov_b32 m0, s86
	s_nop 0
	global_load_lds_dwordx4 v[244:245], off
	s_waitcnt vmcnt(8)
	s_waitcnt lgkmcnt(0)
	s_barrier
; #define PG8_STAGE(bufoff, gbase, voff) do { _Pragma("unroll") for (int _i = 0; _i < 2; ++_i) \
;         __builtin_amdgcn_global_load_lds((const unsigned*)((const char*)(gbase) + (voff)[_i]), (PG8_LAS unsigned*)(lds + (bufoff) + ldsw + _i * 8192), 16, 0, 0); } while (0)
; #define PG8_LDA(dst, b, h) do { _Pragma("unroll") for (int m = 0; m < 4; ++m) _Pragma("unroll") for (int k = 0; k < 2; ++k) dst[m][k] = *(const PG8_LAS bf16x8*)(lds + PG8_SA(b, h) + aoff + m * 2048 + k * 1024); } while (0)
; #define PG8_LDB(dst, b, h) do { _Pragma("unroll") for (int n = 0; n < 2; ++n) _Pragma("unroll") for (int k = 0; k < 2; ++k) dst[n][k] = *(const PG8_LAS bf16x8*)(lds + PG8_SB(b, h) + boff + n * 2048 + k * 1024); } while (0)
; #define PG8_MMA(ai, bj, At, Bt) do { __builtin_amdgcn_s_setprio(1); _Pragma("unroll") for (int m = 0; m < 4; ++m) _Pragma("unroll") for (int n = 0; n < 2; ++n) _Pragma("unroll") for (int k = 0; k < 2; ++k) \
;         acc[ai][bj][m][n] = __builtin_amdgcn_mfma_f32_16x16x32_bf16(Bt[n][k], At[m][k], acc[ai][bj][m][n], 0, 0, 0); __builtin_amdgcn_s_setprio(0); } while (0)
; #define PG8_WAIT_V(n) asm volatile("s_waitcnt vmcnt(" #n ")" ::: "memory")
; #define PG8_WAIT_L(n) asm volatile("s_waitcnt lgkmcnt(" #n ")" ::: "memory")
; #define PG8_BAR __builtin_amdgcn_s_barrier()
; #define PG8_SCHED __builtin_amdgcn_sched_barrier(0)
; template <class Epi, class Sched, bool ALIGN_EPI = false, bool SP2 = false>
; __device__ __forceinline__ void gemm_phase(PG8_LAS unsigned char* lds, const Gemm g, const Sched S, const Epi E) {
;     ...
;             PG8_WAIT_V(8); PG8_WAIT_L(0); PG8_BAR; PG8_MMA(1, 0, At, B0); PG8_MMA(1, 1, At, B1); PG8_BAR; PG8_SCHED;
;             PG8_LDB(B0, 1, 0); PG8_LDB(B1, 1, 1); PG8_SCHED; PG8_LDA(At, 1, 0); PG8_STAGE(PG8_SA(0, 1), a2 + hstep, voffA);
;             PG8_WAIT_V(8); PG8_WAIT_L(0); PG8_BAR; PG8_MMA(0, 0, At, B0); PG8_MMA(0, 1, At, B1); PG8_BAR; PG8_SCHED;
	s_setprio 1
	s_waitcnt lgkmcnt(0)
	v_mfma_f32_16x16x32_bf16 v[62:65], v[154:157], v[202:205], v[62:65]
	v_mfma_f32_16x16x32_bf16 v[58:61], v[162:165], v[202:205], v[58:61]
	v_mfma_f32_16x16x32_bf16 v[46:49], v[154:157], v[210:213], v[46:49]
	v_mfma_f32_16x16x32_bf16 v[42:45], v[162:165], v[210:213], v[42:45]
	v_mfma_f32_16x16x32_bf16 v[30:33], v[154:157], v[218:221], v[30:33]
	v_mfma_f32_16x16x32_bf16 v[26:29], v[162:165], v[218:221], v[26:29]
	v_mfma_f32_16x16x32_bf16 v[14:17], v[154:157], v[226:229], v[14:17]
	v_mfma_f32_16x16x32_bf16 v[10:13], v[162:165], v[226:229], v[10:13]
	v_mfma_f32_16x16x32_bf16 v[62:65], v[158:161], v[206:209], v[62:65]
	v_mfma_f32_16x16x32_bf16 v[58:61], v[166:169], v[206:209], v[58:61]
	v_mfma_f32_16x16x32_bf16 v[46:49], v[158:161], v[214:217], v[46:49]
	v_mfma_f32_16x16x32_bf16 v[42:45], v[166:169], v[214:217], v[42:45]
	v_mfma_f32_16x16x32_bf16 v[30:33], v[158:161], v[222:225], v[30:33]
	v_mfma_f32_16x16x32_bf16 v[26:29], v[166:169], v[222:225], v[26:29]
	v_mfma_f32_16x16x32_bf16 v[14:17], v[158:161], v[230:233], v[14:17]
	v_mfma_f32_16x16x32_bf16 v[10:13], v[166:169], v[230:233], v[10:13]
	s_setprio 0
	s_setprio 1
	v_mfma_f32_16x16x32_bf16 v[54:57], v[170:173], v[202:205], v[54:57]
	v_mfma_f32_16x16x32_bf16 v[50:53], v[182:185], v[202:205], v[50:53]
	v_mfma_f32_16x16x32_bf16 v[38:41], v[170:173], v[210:213], v[38:41]
	v_mfma_f32_16x16x32_bf16 v[34:37], v[182:185], v[210:213], v[34:37]
	v_mfma_f32_16x16x32_bf16 v[22:25], v[170:173], v[218:221], v[22:25]
	v_mfma_f32_16x16x32_bf16 v[18:21], v[182:185], v[218:221], v[18:21]
	v_mfma_f32_16x16x32_bf16 v[6:9], v[170:173], v[226:229], v[6:9]
	v_mfma_f32_16x16x32_bf16 v[2:5], v[182:185], v[226:229], v[2:5]
	v_mfma_f32_16x16x32_bf16 v[54:57], v[174:177], v[206:209], v[54:57]
	v_mfma_f32_16x16x32_bf16 v[50:53], v[198:201], v[206:209], v[50:53]
	v_mfma_f32_16x16x32_bf16 v[38:41], v[174:177], v[214:217], v[38:41]
	v_mfma_f32_16x16x32_bf16 v[34:37], v[198:201], v[214:217], v[34:37]
	v_mfma_f32_16x16x32_bf16 v[22:25], v[174:177], v[222:225], v[22:25]
	v_mfma_f32_16x16x32_bf16 v[18:21], v[198:201], v[222:225], v[18:21]
	v_mfma_f32_16x16x32_bf16 v[6:9], v[174:177], v[230:233], v[6:9]
	v_mfma_f32_16x16x32_bf16 v[2:5], v[198:201], v[230:233], v[2:5]
	s_setprio 0
	s_barrier
	s_add_i32 s20, 0, 0x18000
	v_add_u32_e32 v141, s20, v147
	s_add_i32 s26, 0, 0x1c000
	ds_read_b128 v[154:157], v141
	ds_read_b128 v[158:161], v141 offset:1024
	ds_read_b128 v[162:165], v141 offset:2048
	ds_read_b128 v[166:169], v141 offset:3072
	v_add_u32_e32 v141, s26, v147
	ds_read_b128 v[170:173], v141
	ds_read_b128 v[174:177], v141 offset:1024
	ds_read_b128 v[182:185], v141 offset:2048
	ds_read_b128 v[198:201], v141 offset:3072
	s_add_u32 s22, s74, s52
	s_addc_u32 s23, s75, 0
	s_mov_b32 m0, s87
	v_lshl_add_u64 v[246:247], s[22:23], 0, v[130:131]
	ds_read_b128 v[202:205], v152 offset:32768
	ds_read_b128 v[206:209], v152 offset:33792
	ds_read_b128 v[210:213], v152 offset:34816
	ds_read_b128 v[214:217], v152 offset:35840
	ds_read_b128 v[218:221], v152 offset:36864
	ds_read_b128 v[222:225], v152 offset:37888
	ds_read_b128 v[226:229], v152 offset:38912
	ds_read_b128 v[230:233], v152 offset:39936
	global_load_lds_dwordx4 v[246:247], off
	v_lshl_add_u64 v[246:247], s[22:23], 0, v[132:133]
	s_mov_b32 m0, s88
	s_nop 0
	global_load_lds_dwordx4 v[246:247], off
	s_waitcnt vmcnt(8)
	s_waitcnt lgkmcnt(0)
	s_barrier
	s_setprio 1
	s_waitcnt lgkmcnt(0)
	v_mfma_f32_16x16x32_bf16 v[126:129], v[154:157], v[202:205], v[126:129]
	v_mfma_f32_16x16x32_bf16 v[122:125], v[162:165], v[202:205], v[122:125]
	v_mfma_f32_16x16x32_bf16 v[110:113], v[154:157], v[210:213], v[110:113]
	v_mfma_f32_16x16x32_bf16 v[106:109], v[162:165], v[210:213], v[106:109]
	v_mfma_f32_16x16x32_bf16 v[94:97], v[154:157], v[218:221], v[94:97]
	v_mfma_f32_16x16x32_bf16 v[90:93], v[162:165], v[218:221], v[90:93]
	v_mfma_f32_16x16x32_bf16 v[78:81], v[154:157], v[226:229], v[78:81]
	v_mfma_f32_16x16x32_bf16 v[74:77], v[162:165], v[226:229], v[74:77]
	v_mfma_f32_16x16x32_bf16 v[126:129], v[158:161], v[206:209], v[126:129]
	v_mfma_f32_16x16x32_bf16 v[122:125], v[166:169], v[206:209], v[122:125]
	v_mfma_f32_16x16x32_bf16 v[110:113], v[158:161], v[214:217], v[110:113]
	v_mfma_f32_16x16x32_bf16 v[106:109], v[166:169], v[214:217], v[106:109]
	v_mfma_f32_16x16x32_bf16 v[94:97], v[158:161], v[222:225], v[94:97]
	v_mfma_f32_16x16x32_bf16 v[90:93], v[166:169], v[222:225], v[90:93]
	v_mfma_f32_16x16x32_bf16 v[78:81], v[158:161], v[230:233], v[78:81]
	v_mfma_f32_16x16x32_bf16 v[74:77], v[166:169], v[230:233], v[74:77]
	s_setprio 0
	s_setprio 1
	v_mfma_f32_16x16x32_bf16 v[118:121], v[170:173], v[202:205], v[118:121]
	v_mfma_f32_16x16x32_bf16 v[114:117], v[182:185], v[202:205], v[114:117]
	v_mfma_f32_16x16x32_bf16 v[102:105], v[170:173], v[210:213], v[102:105]
	v_mfma_f32_16x16x32_bf16 v[98:101], v[182:185], v[210:213], v[98:101]
	v_mfma_f32_16x16x32_bf16 v[86:89], v[170:173], v[218:221], v[86:89]
	v_mfma_f32_16x16x32_bf16 v[82:85], v[182:185], v[218:221], v[82:85]
	v_mfma_f32_16x16x32_bf16 v[70:73], v[170:173], v[226:229], v[70:73]
	v_mfma_f32_16x16x32_bf16 v[66:69], v[182:185], v[226:229], v[66:69]
	v_mfma_f32_16x16x32_bf16 v[118:121], v[174:177], v[206:209], v[118:121]
	v_mfma_f32_16x16x32_bf16 v[114:117], v[198:201], v[206:209], v[114:117]
	v_mfma_f32_16x16x32_bf16 v[102:105], v[174:177], v[214:217], v[102:105]
	v_mfma_f32_16x16x32_bf16 v[98:101], v[198:201], v[214:217], v[98:101]
	v_mfma_f32_16x16x32_bf16 v[86:89], v[174:177], v[222:225], v[86:89]
	v_mfma_f32_16x16x32_bf16 v[82:85], v[198:201], v[222:225], v[82:85]
	v_mfma_f32_16x16x32_bf16 v[70:73], v[174:177], v[230:233], v[70:73]
	v_mfma_f32_16x16x32_bf16 v[66:69], v[198:201], v[230:233], v[66:69]
	s_setprio 0
	s_barrier
; #define PG8_STAGE(bufoff, gbase, voff) do { _Pragma("unroll") for (int _i = 0; _i < 2; ++_i) \
;         __builtin_amdgcn_global_load_lds((const unsigned*)((const char*)(gbase) + (voff)[_i]), (PG8_LAS unsigned*)(lds + (bufoff) + ldsw + _i * 8192), 16, 0, 0); } while (0)
; #define PG8_LDA(dst, b, h) do { _Pragma("unroll") for (int m = 0; m < 4; ++m) _Pragma("unroll") for (int k = 0; k < 2; ++k) dst[m][k] = *(const PG8_LAS bf16x8*)(lds + PG8_SA(b, h) + aoff + m * 2048 + k * 1024); } while (0)
; #define PG8_MMA(ai, bj, At, Bt) do { __builtin_amdgcn_s_setprio(1); _Pragma("unroll") for (int m = 0; m < 4; ++m) _Pragma("unroll") for (int n = 0; n < 2; ++n) _Pragma("unroll") for (int k = 0; k < 2; ++k) \
;         acc[ai][bj][m][n] = __builtin_amdgcn_mfma_f32_16x16x32_bf16(Bt[n][k], At[m][k], acc[ai][bj][m][n], 0, 0, 0); __builtin_amdgcn_s_setprio(0); } while (0)
; #define PG8_WAIT_V(n) asm volatile("s_waitcnt vmcnt(" #n ")" ::: "memory")
; #define PG8_WAIT_L(n) asm volatile("s_waitcnt lgkmcnt(" #n ")" ::: "memory")
; #define PG8_BAR __builtin_amdgcn_s_barrier()
; #define PG8_SCHED __builtin_amdgcn_sched_barrier(0)
; template <class Epi, class Sched, bool ALIGN_EPI = false, bool SP2 = false>
; __device__ __forceinline__ void gemm_phase(PG8_LAS unsigned char* lds, const Gemm g, const Sched S, const Epi E) {
;     ...
;             PG8_LDA(At, 1, 1); PG8_STAGE(PG8_SB(1, 0), b3, voffB); PG8_STAGE(PG8_SB(1, 1), b3 + hstep, voffB); PG8_STAGE(PG8_SA(1, 0), a3, voffA);
;             PG8_WAIT_V(8); PG8_WAIT_L(0); PG8_BAR; PG8_MMA(1, 0, At, B0); PG8_MMA(1, 1, At, B1); PG8_BAR; PG8_SCHED;
	s_add_i32 s20, s20, s84
	v_lshl_add_u64 v[234:235], v[234:235], 0, s[12:13]
	s_mov_b32 m0, s20
	ds_read_b128 v[202:205], v152 offset:49152
	ds_read_b128 v[206:209], v152 offset:50176
	ds_read_b128 v[210:213], v152 offset:51200
	ds_read_b128 v[214:217], v152 offset:52224
	ds_read_b128 v[218:221], v152 offset:53248
	ds_read_b128 v[222:225], v152 offset:54272
	ds_read_b128 v[226:229], v152 offset:55296
	ds_read_b128 v[230:233], v152 offset:56320
	global_load_lds_dwordx4 v[234:235], off
	v_lshl_add_u64 v[234:235], v[236:237], 0, s[12:13]
	s_add_i32 m0, s20, 0x2000
	s_add_i32 s20, s26, s84
	global_load_lds_dwordx4 v[234:235], off
	v_lshl_add_u64 v[234:235], v[238:239], 0, s[12:13]
	s_mov_b32 m0, s20
	s_nop 0
	global_load_lds_dwordx4 v[234:235], off
	v_lshl_add_u64 v[234:235], v[240:241], 0, s[12:13]
	s_add_i32 m0, s20, 0x2000
	s_nop 0
	global_load_lds_dwordx4 v[234:235], off
	v_lshl_add_u64 v[234:235], v[242:243], 0, s[12:13]
	s_mov_b32 m0, s3
	s_nop 0
	global_load_lds_dwordx4 v[234:235], off
	v_lshl_add_u64 v[234:235], v[244:245], 0, s[12:13]
	s_mov_b32 m0, s24
	s_nop 0
	global_load_lds_dwordx4 v[234:235], off
	s_waitcnt vmcnt(8)
	s_waitcnt lgkmcnt(0)
	s_barrier
	s_setprio 1
	s_waitcnt lgkmcnt(0)
	v_mfma_f32_16x16x32_bf16 v[62:65], v[154:157], v[202:205], v[62:65]
	v_mfma_f32_16x16x32_bf16 v[58:61], v[162:165], v[202:205], v[58:61]
	v_mfma_f32_16x16x32_bf16 v[46:49], v[154:157], v[210:213], v[46:49]
	v_mfma_f32_16x16x32_bf16 v[42:45], v[162:165], v[210:213], v[42:45]
	v_mfma_f32_16x16x32_bf16 v[30:33], v[154:157], v[218:221], v[30:33]
	v_mfma_f32_16x16x32_bf16 v[26:29], v[162:165], v[218:221], v[26:29]
	v_mfma_f32_16x16x32_bf16 v[14:17], v[154:157], v[226:229], v[14:17]
	v_mfma_f32_16x16x32_bf16 v[10:13], v[162:165], v[226:229], v[10:13]
	v_mfma_f32_16x16x32_bf16 v[62:65], v[158:161], v[206:209], v[62:65]
	v_mfma_f32_16x16x32_bf16 v[58:61], v[166:169], v[206:209], v[58:61]
	v_mfma_f32_16x16x32_bf16 v[46:49], v[158:161], v[214:217], v[46:49]
	v_mfma_f32_16x16x32_bf16 v[42:45], v[166:169], v[214:217], v[42:45]
	v_mfma_f32_16x16x32_bf16 v[30:33], v[158:161], v[222:225], v[30:33]
	v_mfma_f32_16x16x32_bf16 v[26:29], v[166:169], v[222:225], v[26:29]
	v_mfma_f32_16x16x32_bf16 v[14:17], v[158:161], v[230:233], v[14:17]
	v_mfma_f32_16x16x32_bf16 v[10:13], v[166:169], v[230:233], v[10:13]
	s_setprio 0
	s_setprio 1
	v_mfma_f32_16x16x32_bf16 v[54:57], v[170:173], v[202:205], v[54:57]
	v_mfma_f32_16x16x32_bf16 v[50:53], v[182:185], v[202:205], v[50:53]
	v_mfma_f32_16x16x32_bf16 v[38:41], v[170:173], v[210:213], v[38:41]
	v_mfma_f32_16x16x32_bf16 v[34:37], v[182:185], v[210:213], v[34:37]
	v_mfma_f32_16x16x32_bf16 v[22:25], v[170:173], v[218:221], v[22:25]
	v_mfma_f32_16x16x32_bf16 v[18:21], v[182:185], v[218:221], v[18:21]
	v_mfma_f32_16x16x32_bf16 v[6:9], v[170:173], v[226:229], v[6:9]
	v_mfma_f32_16x16x32_bf16 v[2:5], v[182:185], v[226:229], v[2:5]
	v_mfma_f32_16x16x32_bf16 v[54:57], v[174:177], v[206:209], v[54:57]
	v_mfma_f32_16x16x32_bf16 v[50:53], v[198:201], v[206:209], v[50:53]
	v_mfma_f32_16x16x32_bf16 v[38:41], v[174:177], v[214:217], v[38:41]
	v_mfma_f32_16x16x32_bf16 v[34:37], v[198:201], v[214:217], v[34:37]
	v_mfma_f32_16x16x32_bf16 v[22:25], v[174:177], v[222:225], v[22:25]
	v_mfma_f32_16x16x32_bf16 v[18:21], v[198:201], v[222:225], v[18:21]
	v_mfma_f32_16x16x32_bf16 v[6:9], v[174:177], v[230:233], v[6:9]
	v_mfma_f32_16x16x32_bf16 v[2:5], v[198:201], v[230:233], v[2:5]
	s_setprio 0
	s_add_u32 s30, s30, 0x100
	s_addc_u32 s31, s31, 0
	s_add_u32 s14, s14, 0x100
	s_addc_u32 s15, s15, 0
	s_cmp_ge_u32 s21, s80
	s_mov_b32 s20, s21
	s_barrier
	s_cbranch_scc0 .LBB0_224
	s_and_b64 vcc, exec, s[16:17]
	s_cbranch_vccz .LBB0_227
	s_barrier

; #define PG8_STAGE(bufoff, gbase, voff) do { _Pragma("unroll") for (int _i = 0; _i < 2; ++_i) \
;         __builtin_amdgcn_global_load_lds((const unsigned*)((const char*)(gbase) + (voff)[_i]), (PG8_LAS unsigned*)(lds + (bufoff) + ldsw + _i * 8192), 16, 0, 0); } while (0)
; #define PG8_LDA(dst, b, h) do { _Pragma("unroll") for (int m = 0; m < 4; ++m) _Pragma("unroll") for (int k = 0; k < 2; ++k) dst[m][k] = *(const PG8_LAS bf16x8*)(lds + PG8_SA(b, h) + aoff + m * 2048 + k * 1024); } while (0)
; #define PG8_LDB(dst, b, h) do { _Pragma("unroll") for (int n = 0; n < 2; ++n) _Pragma("unroll") for (int k = 0; k < 2; ++k) dst[n][k] = *(const PG8_LAS bf16x8*)(lds + PG8_SB(b, h) + boff + n * 2048 + k * 1024); } while (0)
; #define PG8_MMA(ai, bj, At, Bt) do { __builtin_amdgcn_s_setprio(1); _Pragma("unroll") for (int m = 0; m < 4; ++m) _Pragma("unroll") for (int n = 0; n < 2; ++n) _Pragma("unroll") for (int k = 0; k < 2; ++k) \
;         acc[ai][bj][m][n] = __builtin_amdgcn_mfma_f32_16x16x32_bf16(Bt[n][k], At[m][k], acc[ai][bj][m][n], 0, 0, 0); __builtin_amdgcn_s_setprio(0); } while (0)
; #define PG8_WAIT_V(n) asm volatile("s_waitcnt vmcnt(" #n ")" ::: "memory")
; #define PG8_WAIT_L(n) asm volatile("s_waitcnt lgkmcnt(" #n ")" ::: "memory")
; #define PG8_BAR __builtin_amdgcn_s_barrier()
; #define PG8_SCHED __builtin_amdgcn_sched_barrier(0)
; template <class Epi, class Sched, bool ALIGN_EPI = false, bool SP2 = false>
; __device__ __forceinline__ void gemm_phase(PG8_LAS unsigned char* lds, const Gemm g, const Sched S, const Epi E) {
;     ...
;             const bool last = (t == nt - 2);
;             const char* a1 = cA + (size_t)(t + 1) * kstep;
;             const char* a2 = last ? nA : cA + (size_t)(t + 2) * kstep; const char* b2 = last ? nB : cB + (size_t)(t + 2) * kstep;
;             const char* a3 = a2 + kstep; const char* b3 = b2 + kstep;
;             if (last && has_next) S.a_ready(nxt);
;             if constexpr (SP2) {
;             PG8_LDB(B0, 0, 0); PG8_LDB(B1, 0, 1); PG8_SCHED; PG8_LDA(At, 0, 0); PG8_STAGE(PG8_SA(1, 1), a1 + hstep, voffA);
;             PG8_WAIT_V(8); PG8_WAIT_L(0); PG8_BAR; PG8_MMA(0, 0, At, B0); PG8_MMA(0, 1, At, B1); PG8_BAR; PG8_SCHED;
;             PG8_LDA(At, 0, 1); PG8_STAGE(PG8_SB(0, 0), b2, voffB); PG8_STAGE(PG8_SB(0, 1), b2 + hstep, voffB); PG8_STAGE(PG8_SA(0, 0), a2, voffA);
.LBB0_416:
	v_add_u32_e32 v158, 0x10000, v168
	v_add_u32_e32 v171, 0x14000, v168
	ds_read_b128 v[134:137], v158
	ds_read_b128 v[138:141], v158 offset:1024
	ds_read_b128 v[142:145], v158 offset:2048
	ds_read_b128 v[158:161], v158 offset:3072
	ds_read_b128 v[162:165], v171
	ds_read_b128 v[172:175], v171 offset:1024
	ds_read_b128 v[182:185], v171 offset:2048
	ds_read_b128 v[198:201], v171 offset:3072
	s_add_i32 s3, s14, 2
	s_add_u32 s15, s68, s16
	s_addc_u32 s18, s69, s17
	s_add_u32 s20, s66, s16
	s_addc_u32 s21, s67, s17
	s_add_i32 s22, 0, 0x10000
	s_cmp_eq_u32 s89, s14
	s_cselect_b32 s19, s1, s18
	s_cselect_b32 s18, s0, s15
	s_cselect_b32 s15, s71, s21
	s_cselect_b32 s14, s70, s20
	s_add_i32 s20, 0, 0x14000
	v_lshl_add_u64 v[176:177], s[68:69], 0, v[132:133]
	s_add_i32 m0, s80, 0xc000
	ds_read_b128 v[202:205], v170
	ds_read_b128 v[206:209], v170 offset:1024
	ds_read_b128 v[210:213], v170 offset:2048
	ds_read_b128 v[214:217], v170 offset:3072
	ds_read_b128 v[218:221], v170 offset:4096
	ds_read_b128 v[222:225], v170 offset:5120
	ds_read_b128 v[226:229], v170 offset:6144
	ds_read_b128 v[230:233], v170 offset:7168
	global_load_lds_dwordx4 v[176:177], off
	v_lshl_add_u64 v[176:177], s[68:69], 0, v[130:131]
	s_add_i32 m0, s80, 0xe000
	s_nop 0
	global_load_lds_dwordx4 v[176:177], off
	s_waitcnt vmcnt(8)
	s_waitcnt lgkmcnt(0)
	s_barrier
	s_setprio 1
	s_waitcnt lgkmcnt(0)
	v_mfma_f32_16x16x32_bf16 v[58:61], v[134:137], v[202:205], v[58:61]
	v_mfma_f32_16x16x32_bf16 v[50:53], v[142:145], v[202:205], v[50:53]
	v_mfma_f32_16x16x32_bf16 v[14:17], v[134:137], v[210:213], v[14:17]
	v_mfma_f32_16x16x32_bf16 v[10:13], v[142:145], v[210:213], v[10:13]
	v_mfma_f32_16x16x32_bf16 v[30:33], v[134:137], v[218:221], v[30:33]
	v_mfma_f32_16x16x32_bf16 v[26:29], v[142:145], v[218:221], v[26:29]
	v_mfma_f32_16x16x32_bf16 v[46:49], v[134:137], v[226:229], v[46:49]
	v_mfma_f32_16x16x32_bf16 v[42:45], v[142:145], v[226:229], v[42:45]
	v_mfma_f32_16x16x32_bf16 v[58:61], v[138:141], v[206:209], v[58:61]
	v_mfma_f32_16x16x32_bf16 v[50:53], v[158:161], v[206:209], v[50:53]
	v_mfma_f32_16x16x32_bf16 v[14:17], v[138:141], v[214:217], v[14:17]
	v_mfma_f32_16x16x32_bf16 v[10:13], v[158:161], v[214:217], v[10:13]
	v_mfma_f32_16x16x32_bf16 v[30:33], v[138:141], v[222:225], v[30:33]
	v_mfma_f32_16x16x32_bf16 v[26:29], v[158:161], v[222:225], v[26:29]
	v_mfma_f32_16x16x32_bf16 v[46:49], v[138:141], v[230:233], v[46:49]
	v_mfma_f32_16x16x32_bf16 v[42:45], v[158:161], v[230:233], v[42:45]
	s_setprio 0
	s_setprio 1
	v_mfma_f32_16x16x32_bf16 v[6:9], v[162:165], v[202:205], v[6:9]
	v_mfma_f32_16x16x32_bf16 v[2:5], v[182:185], v[202:205], v[2:5]
	v_mfma_f32_16x16x32_bf16 v[22:25], v[162:165], v[210:213], v[22:25]
	v_mfma_f32_16x16x32_bf16 v[18:21], v[182:185], v[210:213], v[18:21]
	v_mfma_f32_16x16x32_bf16 v[38:41], v[162:165], v[218:221], v[38:41]
	v_mfma_f32_16x16x32_bf16 v[34:37], v[182:185], v[218:221], v[34:37]
	v_mfma_f32_16x16x32_bf16 v[62:65], v[162:165], v[226:229], v[62:65]
	v_mfma_f32_16x16x32_bf16 v[54:57], v[182:185], v[226:229], v[54:57]
	v_mfma_f32_16x16x32_bf16 v[6:9], v[172:175], v[206:209], v[6:9]
	v_mfma_f32_16x16x32_bf16 v[2:5], v[198:201], v[206:209], v[2:5]
	v_mfma_f32_16x16x32_bf16 v[22:25], v[172:175], v[214:217], v[22:25]
	v_mfma_f32_16x16x32_bf16 v[18:21], v[198:201], v[214:217], v[18:21]
	v_mfma_f32_16x16x32_bf16 v[38:41], v[172:175], v[222:225], v[38:41]
	v_mfma_f32_16x16x32_bf16 v[34:37], v[198:201], v[222:225], v[34:37]
	v_mfma_f32_16x16x32_bf16 v[62:65], v[172:175], v[230:233], v[62:65]
	v_mfma_f32_16x16x32_bf16 v[54:57], v[198:201], v[230:233], v[54:57]
	s_setprio 0
	s_barrier
	s_add_i32 s21, s22, s79
	v_lshl_add_u64 v[176:177], s[14:15], 0, v[148:149]
	s_mov_b32 m0, s21
	ds_read_b128 v[202:205], v170 offset:16384
	ds_read_b128 v[206:209], v170 offset:17408
	ds_read_b128 v[210:213], v170 offset:18432
	ds_read_b128 v[214:217], v170 offset:19456
	ds_read_b128 v[218:221], v170 offset:20480
	ds_read_b128 v[222:225], v170 offset:21504
	ds_read_b128 v[226:229], v170 offset:22528
	ds_read_b128 v[230:233], v170 offset:23552
	global_load_lds_dwordx4 v[176:177], off
	s_add_i32 m0, s21, 0x2000
	v_lshl_add_u64 v[234:235], s[14:15], 0, v[152:153]
	s_add_u32 s14, s14, s28
	s_addc_u32 s15, s15, 0
	s_add_i32 s20, s20, s79
	global_load_lds_dwordx4 v[234:235], off
	v_lshl_add_u64 v[236:237], s[14:15], 0, v[148:149]
	s_mov_b32 m0, s20
	v_lshl_add_u64 v[238:239], s[14:15], 0, v[152:153]
	global_load_lds_dwordx4 v[236:237], off
	s_add_i32 m0, s20, 0x2000
	v_lshl_add_u64 v[240:241], s[18:19], 0, v[146:147]
	global_load_lds_dwordx4 v[238:239], off
	s_mov_b32 m0, s80
	v_lshl_add_u64 v[242:243], s[18:19], 0, v[150:151]
	global_load_lds_dwordx4 v[240:241], off
	s_mov_b32 m0, s81
	s_nop 0
	global_load_lds_dwordx4 v[242:243], off
	s_waitcnt vmcnt(8)
	s_waitcnt lgkmcnt(0)
	s_barrier
; #define PG8_STAGE(bufoff, gbase, voff) do { _Pragma("unroll") for (int _i = 0; _i < 2; ++_i) \
;         __builtin_amdgcn_global_load_lds((const unsigned*)((const char*)(gbase) + (voff)[_i]), (PG8_LAS unsigned*)(lds + (bufoff) + ldsw + _i * 8192), 16, 0, 0); } while (0)
; #define PG8_LDA(dst, b, h) do { _Pragma("unroll") for (int m = 0; m < 4; ++m) _Pragma("unroll") for (int k = 0; k < 2; ++k) dst[m][k] = *(const PG8_LAS bf16x8*)(lds + PG8_SA(b, h) + aoff + m * 2048 + k * 1024); } while (0)
; #define PG8_LDB(dst, b, h) do { _Pragma("unroll") for (int n = 0; n < 2; ++n) _Pragma("unroll") for (int k = 0; k < 2; ++k) dst[n][k] = *(const PG8_LAS bf16x8*)(lds + PG8_SB(b, h) + boff + n * 2048 + k * 1024); } while (0)
; #define PG8_MMA(ai, bj, At, Bt) do { __builtin_amdgcn_s_setprio(1); _Pragma("unroll") for (int m = 0; m < 4; ++m) _Pragma("unroll") for (int n = 0; n < 2; ++n) _Pragma("unroll") for (int k = 0; k < 2; ++k) \
;         acc[ai][bj][m][n] = __builtin_amdgcn_mfma_f32_16x16x32_bf16(Bt[n][k], At[m][k], acc[ai][bj][m][n], 0, 0, 0); __builtin_amdgcn_s_setprio(0); } while (0)
; #define PG8_WAIT_V(n) asm volatile("s_waitcnt vmcnt(" #n ")" ::: "memory")
; #define PG8_WAIT_L(n) asm volatile("s_waitcnt lgkmcnt(" #n ")" ::: "memory")
; #define PG8_BAR __builtin_amdgcn_s_barrier()
; #define PG8_SCHED __builtin_amdgcn_sched_barrier(0)
; template <class Epi, class Sched, bool ALIGN_EPI = false, bool SP2 = false>
; __device__ __forceinline__ void gemm_phase(PG8_LAS unsigned char* lds, const Gemm g, const Sched S, const Epi E) {
;     ...
;             PG8_WAIT_V(8); PG8_WAIT_L(0); PG8_BAR; PG8_MMA(1, 0, At, B0); PG8_MMA(1, 1, At, B1); PG8_BAR; PG8_SCHED;
;             PG8_LDB(B0, 1, 0); PG8_LDB(B1, 1, 1); PG8_SCHED; PG8_LDA(At, 1, 0); PG8_STAGE(PG8_SA(0, 1), a2 + hstep, voffA);
;             PG8_WAIT_V(8); PG8_WAIT_L(0); PG8_BAR; PG8_MMA(0, 0, At, B0); PG8_MMA(0, 1, At, B1); PG8_BAR; PG8_SCHED;
	s_setprio 1
	s_waitcnt lgkmcnt(0)
	v_mfma_f32_16x16x32_bf16 v[70:73], v[134:137], v[202:205], v[70:73]
	v_mfma_f32_16x16x32_bf16 v[66:69], v[142:145], v[202:205], v[66:69]
	v_mfma_f32_16x16x32_bf16 v[86:89], v[134:137], v[210:213], v[86:89]
	v_mfma_f32_16x16x32_bf16 v[82:85], v[142:145], v[210:213], v[82:85]
	v_mfma_f32_16x16x32_bf16 v[102:105], v[134:137], v[218:221], v[102:105]
	v_mfma_f32_16x16x32_bf16 v[98:101], v[142:145], v[218:221], v[98:101]
	v_mfma_f32_16x16x32_bf16 v[118:121], v[134:137], v[226:229], v[118:121]
	v_mfma_f32_16x16x32_bf16 v[114:117], v[142:145], v[226:229], v[114:117]
	v_mfma_f32_16x16x32_bf16 v[70:73], v[138:141], v[206:209], v[70:73]
	v_mfma_f32_16x16x32_bf16 v[66:69], v[158:161], v[206:209], v[66:69]
	v_mfma_f32_16x16x32_bf16 v[86:89], v[138:141], v[214:217], v[86:89]
	v_mfma_f32_16x16x32_bf16 v[82:85], v[158:161], v[214:217], v[82:85]
	v_mfma_f32_16x16x32_bf16 v[102:105], v[138:141], v[222:225], v[102:105]
	v_mfma_f32_16x16x32_bf16 v[98:101], v[158:161], v[222:225], v[98:101]
	v_mfma_f32_16x16x32_bf16 v[118:121], v[138:141], v[230:233], v[118:121]
	v_mfma_f32_16x16x32_bf16 v[114:117], v[158:161], v[230:233], v[114:117]
	s_setprio 0
	s_setprio 1
	v_mfma_f32_16x16x32_bf16 v[78:81], v[162:165], v[202:205], v[78:81]
	v_mfma_f32_16x16x32_bf16 v[74:77], v[182:185], v[202:205], v[74:77]
	v_mfma_f32_16x16x32_bf16 v[94:97], v[162:165], v[210:213], v[94:97]
	v_mfma_f32_16x16x32_bf16 v[90:93], v[182:185], v[210:213], v[90:93]
	v_mfma_f32_16x16x32_bf16 v[110:113], v[162:165], v[218:221], v[110:113]
	v_mfma_f32_16x16x32_bf16 v[106:109], v[182:185], v[218:221], v[106:109]
	v_mfma_f32_16x16x32_bf16 v[126:129], v[162:165], v[226:229], v[126:129]
	v_mfma_f32_16x16x32_bf16 v[122:125], v[182:185], v[226:229], v[122:125]
	v_mfma_f32_16x16x32_bf16 v[78:81], v[172:175], v[206:209], v[78:81]
	v_mfma_f32_16x16x32_bf16 v[74:77], v[198:201], v[206:209], v[74:77]
	v_mfma_f32_16x16x32_bf16 v[94:97], v[172:175], v[214:217], v[94:97]
	v_mfma_f32_16x16x32_bf16 v[90:93], v[198:201], v[214:217], v[90:93]
	v_mfma_f32_16x16x32_bf16 v[110:113], v[172:175], v[222:225], v[110:113]
	v_mfma_f32_16x16x32_bf16 v[106:109], v[198:201], v[222:225], v[106:109]
	v_mfma_f32_16x16x32_bf16 v[126:129], v[172:175], v[230:233], v[126:129]
	v_mfma_f32_16x16x32_bf16 v[122:125], v[198:201], v[230:233], v[122:125]
	s_setprio 0
	s_barrier
	s_add_i32 s20, 0, 0x18000
	s_add_i32 s21, 0, 0x1c000
	v_add_u32_e32 v158, s20, v168
	v_add_u32_e32 v171, s21, v168
	ds_read_b128 v[134:137], v158
	ds_read_b128 v[138:141], v158 offset:1024
	ds_read_b128 v[142:145], v158 offset:2048
	ds_read_b128 v[158:161], v158 offset:3072
	ds_read_b128 v[162:165], v171
	ds_read_b128 v[172:175], v171 offset:1024
	ds_read_b128 v[182:185], v171 offset:2048
	ds_read_b128 v[198:201], v171 offset:3072
	s_add_u32 s14, s18, s28
	s_addc_u32 s15, s19, 0
	s_mov_b32 m0, s82
	v_lshl_add_u64 v[244:245], s[14:15], 0, v[146:147]
	ds_read_b128 v[202:205], v170 offset:32768
	ds_read_b128 v[206:209], v170 offset:33792
	ds_read_b128 v[210:213], v170 offset:34816
	ds_read_b128 v[214:217], v170 offset:35840
	ds_read_b128 v[218:221], v170 offset:36864
	ds_read_b128 v[222:225], v170 offset:37888
	ds_read_b128 v[226:229], v170 offset:38912
	ds_read_b128 v[230:233], v170 offset:39936
	global_load_lds_dwordx4 v[244:245], off
	v_lshl_add_u64 v[244:245], s[14:15], 0, v[150:151]
	s_mov_b32 m0, s83
	s_nop 0
	global_load_lds_dwordx4 v[244:245], off
	s_waitcnt vmcnt(8)
	s_waitcnt lgkmcnt(0)
	s_barrier
	s_setprio 1
	s_waitcnt lgkmcnt(0)
	v_mfma_f32_16x16x32_bf16 v[58:61], v[134:137], v[202:205], v[58:61]
	v_mfma_f32_16x16x32_bf16 v[50:53], v[142:145], v[202:205], v[50:53]
	v_mfma_f32_16x16x32_bf16 v[14:17], v[134:137], v[210:213], v[14:17]
	v_mfma_f32_16x16x32_bf16 v[10:13], v[142:145], v[210:213], v[10:13]
	v_mfma_f32_16x16x32_bf16 v[30:33], v[134:137], v[218:221], v[30:33]
	v_mfma_f32_16x16x32_bf16 v[26:29], v[142:145], v[218:221], v[26:29]
	v_mfma_f32_16x16x32_bf16 v[46:49], v[134:137], v[226:229], v[46:49]
	v_mfma_f32_16x16x32_bf16 v[42:45], v[142:145], v[226:229], v[42:45]
	v_mfma_f32_16x16x32_bf16 v[58:61], v[138:141], v[206:209], v[58:61]
	v_mfma_f32_16x16x32_bf16 v[50:53], v[158:161], v[206:209], v[50:53]
	v_mfma_f32_16x16x32_bf16 v[14:17], v[138:141], v[214:217], v[14:17]
	v_mfma_f32_16x16x32_bf16 v[10:13], v[158:161], v[214:217], v[10:13]
	v_mfma_f32_16x16x32_bf16 v[30:33], v[138:141], v[222:225], v[30:33]
	v_mfma_f32_16x16x32_bf16 v[26:29], v[158:161], v[222:225], v[26:29]
	v_mfma_f32_16x16x32_bf16 v[46:49], v[138:141], v[230:233], v[46:49]
	v_mfma_f32_16x16x32_bf16 v[42:45], v[158:161], v[230:233], v[42:45]
	s_setprio 0
	s_setprio 1
	v_mfma_f32_16x16x32_bf16 v[6:9], v[162:165], v[202:205], v[6:9]
	v_mfma_f32_16x16x32_bf16 v[2:5], v[182:185], v[202:205], v[2:5]
	v_mfma_f32_16x16x32_bf16 v[22:25], v[162:165], v[210:213], v[22:25]
	v_mfma_f32_16x16x32_bf16 v[18:21], v[182:185], v[210:213], v[18:21]
	v_mfma_f32_16x16x32_bf16 v[38:41], v[162:165], v[218:221], v[38:41]
	v_mfma_f32_16x16x32_bf16 v[34:37], v[182:185], v[218:221], v[34:37]
	v_mfma_f32_16x16x32_bf16 v[62:65], v[162:165], v[226:229], v[62:65]
	v_mfma_f32_16x16x32_bf16 v[54:57], v[182:185], v[226:229], v[54:57]
	v_mfma_f32_16x16x32_bf16 v[6:9], v[172:175], v[206:209], v[6:9]
	v_mfma_f32_16x16x32_bf16 v[2:5], v[198:201], v[206:209], v[2:5]
	v_mfma_f32_16x16x32_bf16 v[22:25], v[172:175], v[214:217], v[22:25]
	v_mfma_f32_16x16x32_bf16 v[18:21], v[198:201], v[214:217], v[18:21]
	v_mfma_f32_16x16x32_bf16 v[38:41], v[172:175], v[222:225], v[38:41]
	v_mfma_f32_16x16x32_bf16 v[34:37], v[198:201], v[222:225], v[34:37]
	v_mfma_f32_16x16x32_bf16 v[62:65], v[172:175], v[230:233], v[62:65]
	v_mfma_f32_16x16x32_bf16 v[54:57], v[198:201], v[230:233], v[54:57]
	s_setprio 0
	s_barrier
; #define PG8_STAGE(bufoff, gbase, voff) do { _Pragma("unroll") for (int _i = 0; _i < 2; ++_i) \
;         __builtin_amdgcn_global_load_lds((const unsigned*)((const char*)(gbase) + (voff)[_i]), (PG8_LAS unsigned*)(lds + (bufoff) + ldsw + _i * 8192), 16, 0, 0); } while (0)
; #define PG8_LDA(dst, b, h) do { _Pragma("unroll") for (int m = 0; m < 4; ++m) _Pragma("unroll") for (int k = 0; k < 2; ++k) dst[m][k] = *(const PG8_LAS bf16x8*)(lds + PG8_SA(b, h) + aoff + m * 2048 + k * 1024); } while (0)
; #define PG8_MMA(ai, bj, At, Bt) do { __builtin_amdgcn_s_setprio(1); _Pragma("unroll") for (int m = 0; m < 4; ++m) _Pragma("unroll") for (int n = 0; n < 2; ++n) _Pragma("unroll") for (int k = 0; k < 2; ++k) \
;         acc[ai][bj][m][n] = __builtin_amdgcn_mfma_f32_16x16x32_bf16(Bt[n][k], At[m][k], acc[ai][bj][m][n], 0, 0, 0); __builtin_amdgcn_s_setprio(0); } while (0)
; #define PG8_WAIT_V(n) asm volatile("s_waitcnt vmcnt(" #n ")" ::: "memory")
; #define PG8_WAIT_L(n) asm volatile("s_waitcnt lgkmcnt(" #n ")" ::: "memory")
; #define PG8_BAR __builtin_amdgcn_s_barrier()
; #define PG8_SCHED __builtin_amdgcn_sched_barrier(0)
; template <class Epi, class Sched, bool ALIGN_EPI = false, bool SP2 = false>
; __device__ __forceinline__ void gemm_phase(PG8_LAS unsigned char* lds, const Gemm g, const Sched S, const Epi E) {
;     ...
;             PG8_LDA(At, 1, 1); PG8_STAGE(PG8_SB(1, 0), b3, voffB); PG8_STAGE(PG8_SB(1, 1), b3 + hstep, voffB); PG8_STAGE(PG8_SA(1, 0), a3, voffA);
;             PG8_WAIT_V(8); PG8_WAIT_L(0); PG8_BAR; PG8_MMA(1, 0, At, B0); PG8_MMA(1, 1, At, B1); PG8_BAR; PG8_SCHED;
	s_add_i32 s14, s20, s79
	v_lshl_add_u64 v[176:177], v[176:177], 0, s[12:13]
	s_mov_b32 m0, s14
	ds_read_b128 v[202:205], v170 offset:49152
	ds_read_b128 v[206:209], v170 offset:50176
	ds_read_b128 v[210:213], v170 offset:51200
	ds_read_b128 v[214:217], v170 offset:52224
	ds_read_b128 v[218:221], v170 offset:53248
	ds_read_b128 v[222:225], v170 offset:54272
	ds_read_b128 v[226:229], v170 offset:55296
	ds_read_b128 v[230:233], v170 offset:56320
	global_load_lds_dwordx4 v[176:177], off
	v_lshl_add_u64 v[176:177], v[234:235], 0, s[12:13]
	s_add_i32 m0, s14, 0x2000
	s_add_i32 s14, s21, s79
	global_load_lds_dwordx4 v[176:177], off
	v_lshl_add_u64 v[176:177], v[236:237], 0, s[12:13]
	s_mov_b32 m0, s14
	s_nop 0
	global_load_lds_dwordx4 v[176:177], off
	v_lshl_add_u64 v[176:177], v[238:239], 0, s[12:13]
	s_add_i32 m0, s14, 0x2000
	s_nop 0
	global_load_lds_dwordx4 v[176:177], off
	v_lshl_add_u64 v[176:177], v[240:241], 0, s[12:13]
	s_mov_b32 m0, s84
	s_nop 0
	global_load_lds_dwordx4 v[176:177], off
	v_lshl_add_u64 v[176:177], v[242:243], 0, s[12:13]
	s_mov_b32 m0, s85
	s_nop 0
	global_load_lds_dwordx4 v[176:177], off
	s_waitcnt vmcnt(8)
	s_waitcnt lgkmcnt(0)
	s_barrier
	s_setprio 1
	s_waitcnt lgkmcnt(0)
	v_mfma_f32_16x16x32_bf16 v[70:73], v[134:137], v[202:205], v[70:73]
	v_mfma_f32_16x16x32_bf16 v[66:69], v[142:145], v[202:205], v[66:69]
	v_mfma_f32_16x16x32_bf16 v[86:89], v[134:137], v[210:213], v[86:89]
	v_mfma_f32_16x16x32_bf16 v[82:85], v[142:145], v[210:213], v[82:85]
	v_mfma_f32_16x16x32_bf16 v[102:105], v[134:137], v[218:221], v[102:105]
	v_mfma_f32_16x16x32_bf16 v[98:101], v[142:145], v[218:221], v[98:101]
	v_mfma_f32_16x16x32_bf16 v[118:121], v[134:137], v[226:229], v[118:121]
	v_mfma_f32_16x16x32_bf16 v[114:117], v[142:145], v[226:229], v[114:117]
	v_mfma_f32_16x16x32_bf16 v[70:73], v[138:141], v[206:209], v[70:73]
	v_mfma_f32_16x16x32_bf16 v[66:69], v[158:161], v[206:209], v[66:69]
	v_mfma_f32_16x16x32_bf16 v[86:89], v[138:141], v[214:217], v[86:89]
	v_mfma_f32_16x16x32_bf16 v[82:85], v[158:161], v[214:217], v[82:85]
	v_mfma_f32_16x16x32_bf16 v[102:105], v[138:141], v[222:225], v[102:105]
	v_mfma_f32_16x16x32_bf16 v[98:101], v[158:161], v[222:225], v[98:101]
	v_mfma_f32_16x16x32_bf16 v[118:121], v[138:141], v[230:233], v[118:121]
	v_mfma_f32_16x16x32_bf16 v[114:117], v[158:161], v[230:233], v[114:117]
	s_setprio 0
	s_setprio 1
	v_mfma_f32_16x16x32_bf16 v[78:81], v[162:165], v[202:205], v[78:81]
	v_mfma_f32_16x16x32_bf16 v[74:77], v[182:185], v[202:205], v[74:77]
	v_mfma_f32_16x16x32_bf16 v[94:97], v[162:165], v[210:213], v[94:97]
	v_mfma_f32_16x16x32_bf16 v[90:93], v[182:185], v[210:213], v[90:93]
	v_mfma_f32_16x16x32_bf16 v[110:113], v[162:165], v[218:221], v[110:113]
	v_mfma_f32_16x16x32_bf16 v[106:109], v[182:185], v[218:221], v[106:109]
	v_mfma_f32_16x16x32_bf16 v[126:129], v[162:165], v[226:229], v[126:129]
	v_mfma_f32_16x16x32_bf16 v[122:125], v[182:185], v[226:229], v[122:125]
	v_mfma_f32_16x16x32_bf16 v[78:81], v[172:175], v[206:209], v[78:81]
	v_mfma_f32_16x16x32_bf16 v[74:77], v[198:201], v[206:209], v[74:77]
	v_mfma_f32_16x16x32_bf16 v[94:97], v[172:175], v[214:217], v[94:97]
	v_mfma_f32_16x16x32_bf16 v[90:93], v[198:201], v[214:217], v[90:93]
	v_mfma_f32_16x16x32_bf16 v[110:113], v[172:175], v[222:225], v[110:113]
	v_mfma_f32_16x16x32_bf16 v[106:109], v[198:201], v[222:225], v[106:109]
	v_mfma_f32_16x16x32_bf16 v[126:129], v[172:175], v[230:233], v[126:129]
	v_mfma_f32_16x16x32_bf16 v[122:125], v[198:201], v[230:233], v[122:125]
	s_setprio 0
	s_add_u32 s16, s16, 0x100
	s_addc_u32 s17, s17, 0
	v_lshl_add_u64 v[132:133], v[132:133], 0, s[30:31]
	v_lshl_add_u64 v[130:131], v[130:131], 0, s[30:31]
	s_cmp_ge_u32 s3, s88
	s_mov_b32 s14, s3
	s_barrier
	s_cbranch_scc0 .LBB0_416
	s_and_b64 vcc, exec, s[62:63]
	s_cbranch_vccz .LBB0_419
	s_barrier

; #define PG8_STAGE(bufoff, gbase, voff) do { _Pragma("unroll") for (int _i = 0; _i < 2; ++_i) \
;         __builtin_amdgcn_global_load_lds((const unsigned*)((const char*)(gbase) + (voff)[_i]), (PG8_LAS unsigned*)(lds + (bufoff) + ldsw + _i * 8192), 16, 0, 0); } while (0)
; #define PG8_LDA(dst, b, h) do { _Pragma("unroll") for (int m = 0; m < 4; ++m) _Pragma("unroll") for (int k = 0; k < 2; ++k) dst[m][k] = *(const PG8_LAS bf16x8*)(lds + PG8_SA(b, h) + aoff + m * 2048 + k * 1024); } while (0)
; #define PG8_LDB(dst, b, h) do { _Pragma("unroll") for (int n = 0; n < 2; ++n) _Pragma("unroll") for (int k = 0; k < 2; ++k) dst[n][k] = *(const PG8_LAS bf16x8*)(lds + PG8_SB(b, h) + boff + n * 2048 + k * 1024); } while (0)
; #define PG8_MMA(ai, bj, At, Bt) do { __builtin_amdgcn_s_setprio(1); _Pragma("unroll") for (int m = 0; m < 4; ++m) _Pragma("unroll") for (int n = 0; n < 2; ++n) _Pragma("unroll") for (int k = 0; k < 2; ++k) \
;         acc[ai][bj][m][n] = __builtin_amdgcn_mfma_f32_16x16x32_bf16(Bt[n][k], At[m][k], acc[ai][bj][m][n], 0, 0, 0); __builtin_amdgcn_s_setprio(0); } while (0)
; #define PG8_WAIT_V(n) asm volatile("s_waitcnt vmcnt(" #n ")" ::: "memory")
; #define PG8_WAIT_L(n) asm volatile("s_waitcnt lgkmcnt(" #n ")" ::: "memory")
; #define PG8_BAR __builtin_amdgcn_s_barrier()
; #define PG8_SCHED __builtin_amdgcn_sched_barrier(0)
; template <class Epi, class Sched, bool ALIGN_EPI = false, bool SP2 = false>
; __device__ __forceinline__ void gemm_phase(PG8_LAS unsigned char* lds, const Gemm g, const Sched S, const Epi E) {
;     ...
;             const bool last = (t == nt - 2);
;             const char* a1 = cA + (size_t)(t + 1) * kstep;
;             const char* a2 = last ? nA : cA + (size_t)(t + 2) * kstep; const char* b2 = last ? nB : cB + (size_t)(t + 2) * kstep;
;             const char* a3 = a2 + kstep; const char* b3 = b2 + kstep;
;             if (last && has_next) S.a_ready(nxt);
;             if constexpr (SP2) {
;             PG8_LDB(B0, 0, 0); PG8_LDB(B1, 0, 1); PG8_SCHED; PG8_LDA(At, 0, 0); PG8_STAGE(PG8_SA(1, 1), a1 + hstep, voffA);
;             PG8_WAIT_V(8); PG8_WAIT_L(0); PG8_BAR; PG8_MMA(0, 0, At, B0); PG8_MMA(0, 1, At, B1); PG8_BAR; PG8_SCHED;
;             PG8_LDA(At, 0, 1); PG8_STAGE(PG8_SB(0, 0), b2, voffB); PG8_STAGE(PG8_SB(0, 1), b2 + hstep, voffB); PG8_STAGE(PG8_SA(0, 0), a2, voffA);
.LBB0_538:
	v_add_u32_e32 v155, 0x10000, v152
	ds_read_b128 v[146:149], v155
	ds_read_b128 v[156:159], v155 offset:1024
	ds_read_b128 v[160:163], v155 offset:2048
	ds_read_b128 v[164:167], v155 offset:3072
	v_add_u32_e32 v155, 0x14000, v152
	ds_read_b128 v[168:171], v155
	ds_read_b128 v[172:175], v155 offset:1024
	ds_read_b128 v[182:185], v155 offset:2048
	ds_read_b128 v[198:201], v155 offset:3072
	s_add_i32 s3, s14, 2
	s_add_u32 s15, s68, s16
	s_addc_u32 s18, s69, s17
	s_add_u32 s20, s66, s16
	s_addc_u32 s21, s67, s17
	s_add_i32 s22, 0, 0x10000
	s_cmp_eq_u32 s81, s14
	s_cselect_b32 s19, s1, s18
	s_cselect_b32 s18, s0, s15
	s_cselect_b32 s15, s55, s21
	s_cselect_b32 s14, s54, s20
	s_add_i32 s20, 0, 0x14000
	v_lshl_add_u64 v[176:177], s[68:69], 0, v[144:145]
	s_add_i32 m0, s72, 0xc000
	ds_read_b128 v[202:205], v154
	ds_read_b128 v[206:209], v154 offset:1024
	ds_read_b128 v[210:213], v154 offset:2048
	ds_read_b128 v[214:217], v154 offset:3072
	ds_read_b128 v[218:221], v154 offset:4096
	ds_read_b128 v[222:225], v154 offset:5120
	ds_read_b128 v[226:229], v154 offset:6144
	ds_read_b128 v[230:233], v154 offset:7168
	global_load_lds_dwordx4 v[176:177], off
	v_lshl_add_u64 v[176:177], s[68:69], 0, v[142:143]
	s_add_i32 m0, s72, 0xe000
	s_nop 0
	global_load_lds_dwordx4 v[176:177], off
	s_waitcnt vmcnt(8)
	s_waitcnt lgkmcnt(0)
	s_barrier
	s_setprio 1
	s_waitcnt lgkmcnt(0)
	v_mfma_f32_16x16x32_bf16 v[62:65], v[146:149], v[202:205], v[62:65]
	v_mfma_f32_16x16x32_bf16 v[54:57], v[160:163], v[202:205], v[54:57]
	v_mfma_f32_16x16x32_bf16 v[14:17], v[146:149], v[210:213], v[14:17]
	v_mfma_f32_16x16x32_bf16 v[10:13], v[160:163], v[210:213], v[10:13]
	v_mfma_f32_16x16x32_bf16 v[30:33], v[146:149], v[218:221], v[30:33]
	v_mfma_f32_16x16x32_bf16 v[26:29], v[160:163], v[218:221], v[26:29]
	v_mfma_f32_16x16x32_bf16 v[46:49], v[146:149], v[226:229], v[46:49]
	v_mfma_f32_16x16x32_bf16 v[42:45], v[160:163], v[226:229], v[42:45]
	v_mfma_f32_16x16x32_bf16 v[62:65], v[156:159], v[206:209], v[62:65]
	v_mfma_f32_16x16x32_bf16 v[54:57], v[164:167], v[206:209], v[54:57]
	v_mfma_f32_16x16x32_bf16 v[14:17], v[156:159], v[214:217], v[14:17]
	v_mfma_f32_16x16x32_bf16 v[10:13], v[164:167], v[214:217], v[10:13]
	v_mfma_f32_16x16x32_bf16 v[30:33], v[156:159], v[222:225], v[30:33]
	v_mfma_f32_16x16x32_bf16 v[26:29], v[164:167], v[222:225], v[26:29]
	v_mfma_f32_16x16x32_bf16 v[46:49], v[156:159], v[230:233], v[46:49]
	v_mfma_f32_16x16x32_bf16 v[42:45], v[164:167], v[230:233], v[42:45]
	s_setprio 0
	s_setprio 1
	v_mfma_f32_16x16x32_bf16 v[6:9], v[168:171], v[202:205], v[6:9]
	v_mfma_f32_16x16x32_bf16 v[2:5], v[182:185], v[202:205], v[2:5]
	v_mfma_f32_16x16x32_bf16 v[22:25], v[168:171], v[210:213], v[22:25]
	v_mfma_f32_16x16x32_bf16 v[18:21], v[182:185], v[210:213], v[18:21]
	v_mfma_f32_16x16x32_bf16 v[38:41], v[168:171], v[218:221], v[38:41]
	v_mfma_f32_16x16x32_bf16 v[34:37], v[182:185], v[218:221], v[34:37]
	v_mfma_f32_16x16x32_bf16 v[58:61], v[168:171], v[226:229], v[58:61]
	v_mfma_f32_16x16x32_bf16 v[50:53], v[182:185], v[226:229], v[50:53]
	v_mfma_f32_16x16x32_bf16 v[6:9], v[172:175], v[206:209], v[6:9]
	v_mfma_f32_16x16x32_bf16 v[2:5], v[198:201], v[206:209], v[2:5]
	v_mfma_f32_16x16x32_bf16 v[22:25], v[172:175], v[214:217], v[22:25]
	v_mfma_f32_16x16x32_bf16 v[18:21], v[198:201], v[214:217], v[18:21]
	v_mfma_f32_16x16x32_bf16 v[38:41], v[172:175], v[222:225], v[38:41]
	v_mfma_f32_16x16x32_bf16 v[34:37], v[198:201], v[222:225], v[34:37]
	v_mfma_f32_16x16x32_bf16 v[58:61], v[172:175], v[230:233], v[58:61]
	v_mfma_f32_16x16x32_bf16 v[50:53], v[198:201], v[230:233], v[50:53]
	s_setprio 0
	s_barrier
	s_add_i32 s21, s22, s71
	v_lshl_add_u64 v[176:177], s[14:15], 0, v[0:1]
	s_mov_b32 m0, s21
	ds_read_b128 v[202:205], v154 offset:16384
	ds_read_b128 v[206:209], v154 offset:17408
	ds_read_b128 v[210:213], v154 offset:18432
	ds_read_b128 v[214:217], v154 offset:19456
	ds_read_b128 v[218:221], v154 offset:20480
	ds_read_b128 v[222:225], v154 offset:21504
	ds_read_b128 v[226:229], v154 offset:22528
	ds_read_b128 v[230:233], v154 offset:23552
	global_load_lds_dwordx4 v[176:177], off
	s_add_i32 m0, s21, 0x2000
	v_lshl_add_u64 v[234:235], s[14:15], 0, v[134:135]
	s_add_u32 s14, s14, s28
	s_addc_u32 s15, s15, 0
	s_add_i32 s20, s20, s71
	global_load_lds_dwordx4 v[234:235], off
	v_lshl_add_u64 v[236:237], s[14:15], 0, v[0:1]
	s_mov_b32 m0, s20
	v_lshl_add_u64 v[238:239], s[14:15], 0, v[134:135]
	global_load_lds_dwordx4 v[236:237], off
	s_add_i32 m0, s20, 0x2000
	v_lshl_add_u64 v[240:241], s[18:19], 0, v[130:131]
	global_load_lds_dwordx4 v[238:239], off
	s_mov_b32 m0, s72
	v_lshl_add_u64 v[242:243], s[18:19], 0, v[132:133]
	global_load_lds_dwordx4 v[240:241], off
	s_mov_b32 m0, s73
	s_nop 0
	global_load_lds_dwordx4 v[242:243], off
	s_waitcnt vmcnt(8)
	s_waitcnt lgkmcnt(0)
	s_barrier
; #define PG8_STAGE(bufoff, gbase, voff) do { _Pragma("unroll") for (int _i = 0; _i < 2; ++_i) \
;         __builtin_amdgcn_global_load_lds((const unsigned*)((const char*)(gbase) + (voff)[_i]), (PG8_LAS unsigned*)(lds + (bufoff) + ldsw + _i * 8192), 16, 0, 0); } while (0)
; #define PG8_LDA(dst, b, h) do { _Pragma("unroll") for (int m = 0; m < 4; ++m) _Pragma("unroll") for (int k = 0; k < 2; ++k) dst[m][k] = *(const PG8_LAS bf16x8*)(lds + PG8_SA(b, h) + aoff + m * 2048 + k * 1024); } while (0)
; #define PG8_LDB(dst, b, h) do { _Pragma("unroll") for (int n = 0; n < 2; ++n) _Pragma("unroll") for (int k = 0; k < 2; ++k) dst[n][k] = *(const PG8_LAS bf16x8*)(lds + PG8_SB(b, h) + boff + n * 2048 + k * 1024); } while (0)
; #define PG8_MMA(ai, bj, At, Bt) do { __builtin_amdgcn_s_setprio(1); _Pragma("unroll") for (int m = 0; m < 4; ++m) _Pragma("unroll") for (int n = 0; n < 2; ++n) _Pragma("unroll") for (int k = 0; k < 2; ++k) \
;         acc[ai][bj][m][n] = __builtin_amdgcn_mfma_f32_16x16x32_bf16(Bt[n][k], At[m][k], acc[ai][bj][m][n], 0, 0, 0); __builtin_amdgcn_s_setprio(0); } while (0)
; #define PG8_WAIT_V(n) asm volatile("s_waitcnt vmcnt(" #n ")" ::: "memory")
; #define PG8_WAIT_L(n) asm volatile("s_waitcnt lgkmcnt(" #n ")" ::: "memory")
; #define PG8_BAR __builtin_amdgcn_s_barrier()
; #define PG8_SCHED __builtin_amdgcn_sched_barrier(0)
; template <class Epi, class Sched, bool ALIGN_EPI = false, bool SP2 = false>
; __device__ __forceinline__ void gemm_phase(PG8_LAS unsigned char* lds, const Gemm g, const Sched S, const Epi E) {
;     ...
;             PG8_WAIT_V(8); PG8_WAIT_L(0); PG8_BAR; PG8_MMA(1, 0, At, B0); PG8_MMA(1, 1, At, B1); PG8_BAR; PG8_SCHED;
;             PG8_LDB(B0, 1, 0); PG8_LDB(B1, 1, 1); PG8_SCHED; PG8_LDA(At, 1, 0); PG8_STAGE(PG8_SA(0, 1), a2 + hstep, voffA);
;             PG8_WAIT_V(8); PG8_WAIT_L(0); PG8_BAR; PG8_MMA(0, 0, At, B0); PG8_MMA(0, 1, At, B1); PG8_BAR; PG8_SCHED;
	s_setprio 1
	s_waitcnt lgkmcnt(0)
	v_mfma_f32_16x16x32_bf16 v[70:73], v[146:149], v[202:205], v[70:73]
	v_mfma_f32_16x16x32_bf16 v[66:69], v[160:163], v[202:205], v[66:69]
	v_mfma_f32_16x16x32_bf16 v[86:89], v[146:149], v[210:213], v[86:89]
	v_mfma_f32_16x16x32_bf16 v[82:85], v[160:163], v[210:213], v[82:85]
	v_mfma_f32_16x16x32_bf16 v[102:105], v[146:149], v[218:221], v[102:105]
	v_mfma_f32_16x16x32_bf16 v[98:101], v[160:163], v[218:221], v[98:101]
	v_mfma_f32_16x16x32_bf16 v[118:121], v[146:149], v[226:229], v[118:121]
	v_mfma_f32_16x16x32_bf16 v[114:117], v[160:163], v[226:229], v[114:117]
	v_mfma_f32_16x16x32_bf16 v[70:73], v[156:159], v[206:209], v[70:73]
	v_mfma_f32_16x16x32_bf16 v[66:69], v[164:167], v[206:209], v[66:69]
	v_mfma_f32_16x16x32_bf16 v[86:89], v[156:159], v[214:217], v[86:89]
	v_mfma_f32_16x16x32_bf16 v[82:85], v[164:167], v[214:217], v[82:85]
	v_mfma_f32_16x16x32_bf16 v[102:105], v[156:159], v[222:225], v[102:105]
	v_mfma_f32_16x16x32_bf16 v[98:101], v[164:167], v[222:225], v[98:101]
	v_mfma_f32_16x16x32_bf16 v[118:121], v[156:159], v[230:233], v[118:121]
	v_mfma_f32_16x16x32_bf16 v[114:117], v[164:167], v[230:233], v[114:117]
	s_setprio 0
	s_setprio 1
	v_mfma_f32_16x16x32_bf16 v[78:81], v[168:171], v[202:205], v[78:81]
	v_mfma_f32_16x16x32_bf16 v[74:77], v[182:185], v[202:205], v[74:77]
	v_mfma_f32_16x16x32_bf16 v[94:97], v[168:171], v[210:213], v[94:97]
	v_mfma_f32_16x16x32_bf16 v[90:93], v[182:185], v[210:213], v[90:93]
	v_mfma_f32_16x16x32_bf16 v[110:113], v[168:171], v[218:221], v[110:113]
	v_mfma_f32_16x16x32_bf16 v[106:109], v[182:185], v[218:221], v[106:109]
	v_mfma_f32_16x16x32_bf16 v[126:129], v[168:171], v[226:229], v[126:129]
	v_mfma_f32_16x16x32_bf16 v[122:125], v[182:185], v[226:229], v[122:125]
	v_mfma_f32_16x16x32_bf16 v[78:81], v[172:175], v[206:209], v[78:81]
	v_mfma_f32_16x16x32_bf16 v[74:77], v[198:201], v[206:209], v[74:77]
	v_mfma_f32_16x16x32_bf16 v[94:97], v[172:175], v[214:217], v[94:97]
	v_mfma_f32_16x16x32_bf16 v[90:93], v[198:201], v[214:217], v[90:93]
	v_mfma_f32_16x16x32_bf16 v[110:113], v[172:175], v[222:225], v[110:113]
	v_mfma_f32_16x16x32_bf16 v[106:109], v[198:201], v[222:225], v[106:109]
	v_mfma_f32_16x16x32_bf16 v[126:129], v[172:175], v[230:233], v[126:129]
	v_mfma_f32_16x16x32_bf16 v[122:125], v[198:201], v[230:233], v[122:125]
	s_setprio 0
	s_barrier
	s_add_i32 s20, 0, 0x18000
	v_add_u32_e32 v155, s20, v152
	s_add_i32 s21, 0, 0x1c000
	ds_read_b128 v[146:149], v155
	ds_read_b128 v[156:159], v155 offset:1024
	ds_read_b128 v[160:163], v155 offset:2048
	ds_read_b128 v[164:167], v155 offset:3072
	v_add_u32_e32 v155, s21, v152
	ds_read_b128 v[168:171], v155
	ds_read_b128 v[172:175], v155 offset:1024
	ds_read_b128 v[182:185], v155 offset:2048
	ds_read_b128 v[198:201], v155 offset:3072
	s_add_u32 s14, s18, s28
	s_addc_u32 s15, s19, 0
	s_mov_b32 m0, s74
	v_lshl_add_u64 v[244:245], s[14:15], 0, v[130:131]
	ds_read_b128 v[202:205], v154 offset:32768
	ds_read_b128 v[206:209], v154 offset:33792
	ds_read_b128 v[210:213], v154 offset:34816
	ds_read_b128 v[214:217], v154 offset:35840
	ds_read_b128 v[218:221], v154 offset:36864
	ds_read_b128 v[222:225], v154 offset:37888
	ds_read_b128 v[226:229], v154 offset:38912
	ds_read_b128 v[230:233], v154 offset:39936
	global_load_lds_dwordx4 v[244:245], off
	v_lshl_add_u64 v[244:245], s[14:15], 0, v[132:133]
	s_mov_b32 m0, s75
	s_nop 0
	global_load_lds_dwordx4 v[244:245], off
	s_waitcnt vmcnt(8)
	s_waitcnt lgkmcnt(0)
	s_barrier
	s_setprio 1
	s_waitcnt lgkmcnt(0)
	v_mfma_f32_16x16x32_bf16 v[62:65], v[146:149], v[202:205], v[62:65]
	v_mfma_f32_16x16x32_bf16 v[54:57], v[160:163], v[202:205], v[54:57]
	v_mfma_f32_16x16x32_bf16 v[14:17], v[146:149], v[210:213], v[14:17]
	v_mfma_f32_16x16x32_bf16 v[10:13], v[160:163], v[210:213], v[10:13]
	v_mfma_f32_16x16x32_bf16 v[30:33], v[146:149], v[218:221], v[30:33]
	v_mfma_f32_16x16x32_bf16 v[26:29], v[160:163], v[218:221], v[26:29]
	v_mfma_f32_16x16x32_bf16 v[46:49], v[146:149], v[226:229], v[46:49]
	v_mfma_f32_16x16x32_bf16 v[42:45], v[160:163], v[226:229], v[42:45]
	v_mfma_f32_16x16x32_bf16 v[62:65], v[156:159], v[206:209], v[62:65]
	v_mfma_f32_16x16x32_bf16 v[54:57], v[164:167], v[206:209], v[54:57]
	v_mfma_f32_16x16x32_bf16 v[14:17], v[156:159], v[214:217], v[14:17]
	v_mfma_f32_16x16x32_bf16 v[10:13], v[164:167], v[214:217], v[10:13]
	v_mfma_f32_16x16x32_bf16 v[30:33], v[156:159], v[222:225], v[30:33]
	v_mfma_f32_16x16x32_bf16 v[26:29], v[164:167], v[222:225], v[26:29]
	v_mfma_f32_16x16x32_bf16 v[46:49], v[156:159], v[230:233], v[46:49]
	v_mfma_f32_16x16x32_bf16 v[42:45], v[164:167], v[230:233], v[42:45]
	s_setprio 0
	s_setprio 1
	v_mfma_f32_16x16x32_bf16 v[6:9], v[168:171], v[202:205], v[6:9]
	v_mfma_f32_16x16x32_bf16 v[2:5], v[182:185], v[202:205], v[2:5]
	v_mfma_f32_16x16x32_bf16 v[22:25], v[168:171], v[210:213], v[22:25]
	v_mfma_f32_16x16x32_bf16 v[18:21], v[182:185], v[210:213], v[18:21]
	v_mfma_f32_16x16x32_bf16 v[38:41], v[168:171], v[218:221], v[38:41]
	v_mfma_f32_16x16x32_bf16 v[34:37], v[182:185], v[218:221], v[34:37]
	v_mfma_f32_16x16x32_bf16 v[58:61], v[168:171], v[226:229], v[58:61]
	v_mfma_f32_16x16x32_bf16 v[50:53], v[182:185], v[226:229], v[50:53]
	v_mfma_f32_16x16x32_bf16 v[6:9], v[172:175], v[206:209], v[6:9]
	v_mfma_f32_16x16x32_bf16 v[2:5], v[198:201], v[206:209], v[2:5]
	v_mfma_f32_16x16x32_bf16 v[22:25], v[172:175], v[214:217], v[22:25]
	v_mfma_f32_16x16x32_bf16 v[18:21], v[198:201], v[214:217], v[18:21]
	v_mfma_f32_16x16x32_bf16 v[38:41], v[172:175], v[222:225], v[38:41]
	v_mfma_f32_16x16x32_bf16 v[34:37], v[198:201], v[222:225], v[34:37]
	v_mfma_f32_16x16x32_bf16 v[58:61], v[172:175], v[230:233], v[58:61]
	v_mfma_f32_16x16x32_bf16 v[50:53], v[198:201], v[230:233], v[50:53]
	s_setprio 0
	s_barrier
; #define PG8_STAGE(bufoff, gbase, voff) do { _Pragma("unroll") for (int _i = 0; _i < 2; ++_i) \
;         __builtin_amdgcn_global_load_lds((const unsigned*)((const char*)(gbase) + (voff)[_i]), (PG8_LAS unsigned*)(lds + (bufoff) + ldsw + _i * 8192), 16, 0, 0); } while (0)
; #define PG8_LDA(dst, b, h) do { _Pragma("unroll") for (int m = 0; m < 4; ++m) _Pragma("unroll") for (int k = 0; k < 2; ++k) dst[m][k] = *(const PG8_LAS bf16x8*)(lds + PG8_SA(b, h) + aoff + m * 2048 + k * 1024); } while (0)
; #define PG8_MMA(ai, bj, At, Bt) do { __builtin_amdgcn_s_setprio(1); _Pragma("unroll") for (int m = 0; m < 4; ++m) _Pragma("unroll") for (int n = 0; n < 2; ++n) _Pragma("unroll") for (int k = 0; k < 2; ++k) \
;         acc[ai][bj][m][n] = __builtin_amdgcn_mfma_f32_16x16x32_bf16(Bt[n][k], At[m][k], acc[ai][bj][m][n], 0, 0, 0); __builtin_amdgcn_s_setprio(0); } while (0)
; #define PG8_WAIT_V(n) asm volatile("s_waitcnt vmcnt(" #n ")" ::: "memory")
; #define PG8_WAIT_L(n) asm volatile("s_waitcnt lgkmcnt(" #n ")" ::: "memory")
; #define PG8_BAR __builtin_amdgcn_s_barrier()
; #define PG8_SCHED __builtin_amdgcn_sched_barrier(0)
; template <class Epi, class Sched, bool ALIGN_EPI = false, bool SP2 = false>
; __device__ __forceinline__ void gemm_phase(PG8_LAS unsigned char* lds, const Gemm g, const Sched S, const Epi E) {
;     ...
;             PG8_LDA(At, 1, 1); PG8_STAGE(PG8_SB(1, 0), b3, voffB); PG8_STAGE(PG8_SB(1, 1), b3 + hstep, voffB); PG8_STAGE(PG8_SA(1, 0), a3, voffA);
;             PG8_WAIT_V(8); PG8_WAIT_L(0); PG8_BAR; PG8_MMA(1, 0, At, B0); PG8_MMA(1, 1, At, B1); PG8_BAR; PG8_SCHED;
	s_add_i32 s14, s20, s71
	v_lshl_add_u64 v[176:177], v[176:177], 0, s[12:13]
	s_mov_b32 m0, s14
	ds_read_b128 v[202:205], v154 offset:49152
	ds_read_b128 v[206:209], v154 offset:50176
	ds_read_b128 v[210:213], v154 offset:51200
	ds_read_b128 v[214:217], v154 offset:52224
	ds_read_b128 v[218:221], v154 offset:53248
	ds_read_b128 v[222:225], v154 offset:54272
	ds_read_b128 v[226:229], v154 offset:55296
	ds_read_b128 v[230:233], v154 offset:56320
	global_load_lds_dwordx4 v[176:177], off
	v_lshl_add_u64 v[176:177], v[234:235], 0, s[12:13]
	s_add_i32 m0, s14, 0x2000
	s_add_i32 s14, s21, s71
	global_load_lds_dwordx4 v[176:177], off
	v_lshl_add_u64 v[176:177], v[236:237], 0, s[12:13]
	s_mov_b32 m0, s14
	s_nop 0
	global_load_lds_dwordx4 v[176:177], off
	v_lshl_add_u64 v[176:177], v[238:239], 0, s[12:13]
	s_add_i32 m0, s14, 0x2000
	s_nop 0
	global_load_lds_dwordx4 v[176:177], off
	v_lshl_add_u64 v[176:177], v[240:241], 0, s[12:13]
	s_mov_b32 m0, s77
	s_nop 0
	global_load_lds_dwordx4 v[176:177], off
	v_lshl_add_u64 v[176:177], v[242:243], 0, s[12:13]
	s_mov_b32 m0, s78
	s_nop 0
	global_load_lds_dwordx4 v[176:177], off
	s_waitcnt vmcnt(8)
	s_waitcnt lgkmcnt(0)
	s_barrier
	s_setprio 1
	s_waitcnt lgkmcnt(0)
	v_mfma_f32_16x16x32_bf16 v[70:73], v[146:149], v[202:205], v[70:73]
	v_mfma_f32_16x16x32_bf16 v[66:69], v[160:163], v[202:205], v[66:69]
	v_mfma_f32_16x16x32_bf16 v[86:89], v[146:149], v[210:213], v[86:89]
	v_mfma_f32_16x16x32_bf16 v[82:85], v[160:163], v[210:213], v[82:85]
	v_mfma_f32_16x16x32_bf16 v[102:105], v[146:149], v[218:221], v[102:105]
	v_mfma_f32_16x16x32_bf16 v[98:101], v[160:163], v[218:221], v[98:101]
	v_mfma_f32_16x16x32_bf16 v[118:121], v[146:149], v[226:229], v[118:121]
	v_mfma_f32_16x16x32_bf16 v[114:117], v[160:163], v[226:229], v[114:117]
	v_mfma_f32_16x16x32_bf16 v[70:73], v[156:159], v[206:209], v[70:73]
	v_mfma_f32_16x16x32_bf16 v[66:69], v[164:167], v[206:209], v[66:69]
	v_mfma_f32_16x16x32_bf16 v[86:89], v[156:159], v[214:217], v[86:89]
	v_mfma_f32_16x16x32_bf16 v[82:85], v[164:167], v[214:217], v[82:85]
	v_mfma_f32_16x16x32_bf16 v[102:105], v[156:159], v[222:225], v[102:105]
	v_mfma_f32_16x16x32_bf16 v[98:101], v[164:167], v[222:225], v[98:101]
	v_mfma_f32_16x16x32_bf16 v[118:121], v[156:159], v[230:233], v[118:121]
	v_mfma_f32_16x16x32_bf16 v[114:117], v[164:167], v[230:233], v[114:117]
	s_setprio 0
	s_setprio 1
	v_mfma_f32_16x16x32_bf16 v[78:81], v[168:171], v[202:205], v[78:81]
	v_mfma_f32_16x16x32_bf16 v[74:77], v[182:185], v[202:205], v[74:77]
	v_mfma_f32_16x16x32_bf16 v[94:97], v[168:171], v[210:213], v[94:97]
	v_mfma_f32_16x16x32_bf16 v[90:93], v[182:185], v[210:213], v[90:93]
	v_mfma_f32_16x16x32_bf16 v[110:113], v[168:171], v[218:221], v[110:113]
	v_mfma_f32_16x16x32_bf16 v[106:109], v[182:185], v[218:221], v[106:109]
	v_mfma_f32_16x16x32_bf16 v[126:129], v[168:171], v[226:229], v[126:129]
	v_mfma_f32_16x16x32_bf16 v[122:125], v[182:185], v[226:229], v[122:125]
	v_mfma_f32_16x16x32_bf16 v[78:81], v[172:175], v[206:209], v[78:81]
	v_mfma_f32_16x16x32_bf16 v[74:77], v[198:201], v[206:209], v[74:77]
	v_mfma_f32_16x16x32_bf16 v[94:97], v[172:175], v[214:217], v[94:97]
	v_mfma_f32_16x16x32_bf16 v[90:93], v[198:201], v[214:217], v[90:93]
	v_mfma_f32_16x16x32_bf16 v[110:113], v[172:175], v[222:225], v[110:113]
	v_mfma_f32_16x16x32_bf16 v[106:109], v[198:201], v[222:225], v[106:109]
	v_mfma_f32_16x16x32_bf16 v[126:129], v[172:175], v[230:233], v[126:129]
	v_mfma_f32_16x16x32_bf16 v[122:125], v[198:201], v[230:233], v[122:125]
	s_setprio 0
	s_add_u32 s16, s16, 0x100
	s_addc_u32 s17, s17, 0
	v_lshl_add_u64 v[144:145], v[144:145], 0, s[88:89]
	v_lshl_add_u64 v[142:143], v[142:143], 0, s[88:89]
	s_cmp_ge_u32 s3, s76
	s_mov_b32 s14, s3
	s_barrier
	s_cbranch_scc0 .LBB0_538
	s_and_b64 vcc, exec, s[62:63]
	s_cbranch_vccz .LBB0_541
	s_barrier
